# counted vmcnt in gemm commit/issue + rglru ssq-sum de-serialized + rglru counted vmcnt
# baseline (speedup 1.0000x reference)
;     __device__ __forceinline__ void issue(const Unit& u, Pre& p) const {
;         int t = threadIdx.x; asm volatile("" : "+v"(t));
;         if (t < 256) { gp_t g = (gp_t)(ssq + (size_t)(u.pm * BM + t) * 16); p.a = g[0]; p.b = g[1]; p.c = g[2]; p.d = g[3]; }
;     }
.LBB0_124:
	s_andn2_b64 vcc, exec, s[2:3]
	s_cbranch_vccnz .LBB0_128
	v_mov_b32_e32 v158, v204
	s_nop 0
	v_cmp_gt_i32_e32 vcc, s68, v158
	s_and_saveexec_b64 s[2:3], vcc
	s_cbranch_execz .LBB0_127
	s_nop 0
	v_lshl_add_u32 v2, s12, 8, v158
	v_ashrrev_i32_e32 v3, 31, v2
	v_lshlrev_b64 v[2:3], 6, v[2:3]
	v_lshl_add_u64 v[14:15], s[4:5], 0, v[2:3]
	global_load_dwordx4 v[2:5], v[14:15], off offset:48
	global_load_dwordx4 v[6:9], v[14:15], off offset:32
	global_load_dwordx4 v[10:13], v[14:15], off offset:16
	s_nop 0
	global_load_dwordx4 v[14:17], v[14:15], off

; __device__ __forceinline__ unsigned cvt_pk_bf16(float lo, float hi) { unsigned r; asm volatile("v_cvt_pk_bf16_f32 %0, %1, %2" : "=v"(r) : "v"(lo), "v"(hi)); return r; }
; __device__ __forceinline__ float silu_f(float g) { return g * __builtin_amdgcn_rcpf(1.0f + __expf(-g)); }
;     __device__ __forceinline__ void operator()(const f32x4 (&acc)[2][2][4][2], const Unit& u, int ui, int wr, int wc, int fr, int fq) const {
;         const int row0 = u.pm * BM + wr * 64 + fr, col0 = u.pn * HALF + wc * 32 + 8 * fq;
; #pragma unroll
;         for (int ai = 0; ai < 2; ++ai)
; #pragma unroll
;             for (int m = 0; m < 4; ++m) {
;                 const int row = row0 + ai * HALF + m * 16;
;                 const float s = rsb[(ui & 1) * 256 + ai * HALF + wr * 64 + m * 16 + fr];
;                 f32x4 g0 = acc[ai][0][m][0] * s, g1 = acc[ai][0][m][1] * s, u0 = acc[ai][1][m][0] * s, u1 = acc[ai][1][m][1] * s;
;                 u32x4 w;
;                 w.x = cvt_pk_bf16(silu_f(g0[0]) * u0[0], silu_f(g0[1]) * u0[1]); w.y = cvt_pk_bf16(silu_f(g0[2]) * u0[2], silu_f(g0[3]) * u0[3]);
;                 w.z = cvt_pk_bf16(silu_f(g1[0]) * u1[0], silu_f(g1[1]) * u1[1]); w.w = cvt_pk_bf16(silu_f(g1[2]) * u1[2], silu_f(g1[3]) * u1[3]);
;                 *(u32x4*)(H + (size_t)row * ldh + col0) = w;
.LBB0_128:
	s_lshl_b32 s2, s61, 10
	s_and_b32 s2, s2, 0x400
	v_add_u32_e32 v165, s2, v162
	ds_read_b32 v166, v165
	v_lshl_or_b32 v158, s45, 7, v161
	v_lshl_add_u32 v164, s44, 8, v1
	v_ashrrev_i32_e32 v159, 31, v158
	s_cmp_eq_u32 s61, 10
	s_waitcnt lgkmcnt(0)
	v_pk_mul_f32 v[142:143], v[142:143], v[166:167] op_sel_hi:[1,0]
	v_pk_mul_f32 v[144:145], v[144:145], v[166:167] op_sel_hi:[1,0]
	v_pk_mul_f32 v[140:141], v[140:141], v[166:167] op_sel_hi:[1,0]
	v_pk_mul_f32 v[138:139], v[138:139], v[166:167] op_sel_hi:[1,0]
	v_pk_mul_f32 v[136:137], v[136:137], v[166:167] op_sel_hi:[1,0]
	v_pk_mul_f32 v[134:135], v[134:135], v[166:167] op_sel_hi:[1,0]
	v_mul_f32_e32 v167, 0xbfb8aa3b, v142
	v_exp_f32_e32 v167, v167
	v_mul_f32_e32 v168, 0xbfb8aa3b, v143
	v_exp_f32_e32 v168, v168
	v_pk_mul_f32 v[132:133], v[132:133], v[166:167] op_sel_hi:[1,0]
	v_add_f32_e32 v167, 1.0, v167
	v_rcp_f32_e32 v167, v167
	v_add_f32_e32 v168, 1.0, v168
	v_rcp_f32_e32 v168, v168
	v_mul_f32_e32 v142, v142, v167
	v_mul_f32_e32 v134, v134, v142
	v_mul_f32_e32 v142, v143, v168
	v_mul_f32_e32 v143, 0xbfb8aa3b, v144
	v_exp_f32_e32 v143, v143
	v_pk_mul_f32 v[130:131], v[130:131], v[166:167] op_sel_hi:[1,0]
	v_mul_f32_e32 v166, 0xbfb8aa3b, v145
	v_exp_f32_e32 v166, v166
	v_mul_f32_e32 v135, v135, v142
	v_add_f32_e32 v142, 1.0, v143
	v_rcp_f32_e32 v142, v142
	v_add_f32_e32 v143, 1.0, v166
	v_rcp_f32_e32 v143, v143
	v_cvt_pk_bf16_f32 v134, v134, v135
	v_mul_f32_e32 v135, v144, v142
	v_mul_f32_e32 v142, 0xbfb8aa3b, v138
	v_exp_f32_e32 v142, v142
	v_mul_f32_e32 v135, v136, v135
	v_mul_f32_e32 v136, v145, v143
	v_mul_f32_e32 v143, 0xbfb8aa3b, v139
	v_exp_f32_e32 v143, v143
	v_mul_f32_e32 v136, v137, v136
	v_add_f32_e32 v137, 1.0, v142
	v_rcp_f32_e32 v137, v137
	v_add_f32_e32 v142, 1.0, v143
	v_rcp_f32_e32 v142, v142
	v_cvt_pk_bf16_f32 v135, v135, v136
	v_mul_f32_e32 v136, v138, v137
	v_mul_f32_e32 v137, 0xbfb8aa3b, v140
	v_exp_f32_e32 v137, v137
	v_mul_f32_e32 v138, 0xbfb8aa3b, v141
	v_exp_f32_e32 v138, v138
	v_mul_f32_e32 v130, v130, v136
	v_mul_f32_e32 v136, v139, v142
	v_mul_f32_e32 v131, v131, v136
	v_add_f32_e32 v136, 1.0, v137
	v_rcp_f32_e32 v137, v136
	v_add_f32_e32 v136, 1.0, v138
	v_rcp_f32_e32 v138, v136
	v_cvt_pk_bf16_f32 v136, v130, v131
	v_mul_f32_e32 v130, v140, v137
	v_mul_f32_e32 v130, v132, v130
	v_mul_f32_e32 v131, v141, v138
	v_mul_f32_e32 v131, v133, v131
	v_cvt_pk_bf16_f32 v137, v130, v131
	ds_read_b32 v140, v165 offset:64
	v_mov_b64_e32 v[130:131], s[8:9]
	v_mad_i64_i32 v[138:139], s[2:3], v164, s71, v[130:131]
	v_lshlrev_b64 v[132:133], 1, v[158:159]
	v_lshl_add_u64 v[138:139], v[138:139], 0, v[132:133]
	s_waitcnt lgkmcnt(0)
	v_pk_mul_f32 v[126:127], v[126:127], v[140:141] op_sel_hi:[1,0]
	global_store_dwordx4 v[138:139], v[134:137], off
	v_pk_mul_f32 v[128:129], v[128:129], v[140:141] op_sel_hi:[1,0]
	v_pk_mul_f32 v[118:119], v[118:119], v[140:141] op_sel_hi:[1,0]
	v_mul_f32_e32 v134, 0xbfb8aa3b, v126
	v_exp_f32_e32 v137, v134
	v_mul_f32_e32 v134, 0xbfb8aa3b, v127
	v_exp_f32_e32 v138, v134
	v_pk_mul_f32 v[134:135], v[116:117], v[140:141] op_sel_hi:[1,0]
	v_add_f32_e32 v116, 1.0, v137
	v_rcp_f32_e32 v137, v116
	v_add_f32_e32 v116, 1.0, v138
	v_rcp_f32_e32 v138, v116
	v_pk_mul_f32 v[116:117], v[114:115], v[140:141] op_sel_hi:[1,0]
	v_mul_f32_e32 v114, v126, v137
	v_mul_f32_e32 v114, v118, v114
	v_mul_f32_e32 v118, 0xbfb8aa3b, v128
	v_mul_f32_e32 v126, 0xbfb8aa3b, v129
	v_exp_f32_e32 v118, v118
	v_exp_f32_e32 v126, v126
	v_mul_f32_e32 v115, v127, v138
	v_mul_f32_e32 v115, v119, v115
	v_add_f32_e32 v118, 1.0, v118
	v_add_f32_e32 v119, 1.0, v126
	v_rcp_f32_e32 v118, v118
	v_rcp_f32_e32 v119, v119
	v_pk_mul_f32 v[122:123], v[122:123], v[140:141] op_sel_hi:[1,0]
	v_pk_mul_f32 v[120:121], v[120:121], v[140:141] op_sel_hi:[1,0]
	v_cvt_pk_bf16_f32 v114, v114, v115
	v_mul_f32_e32 v115, v128, v118
	v_mul_f32_e32 v118, v129, v119
	v_mul_f32_e32 v119, 0xbfb8aa3b, v122
	v_mul_f32_e32 v115, v120, v115
	v_exp_f32_e32 v119, v119
	v_mul_f32_e32 v120, 0xbfb8aa3b, v123
	v_exp_f32_e32 v120, v120
	v_mul_f32_e32 v118, v121, v118
	v_add_f32_e32 v119, 1.0, v119
	v_rcp_f32_e32 v119, v119
	v_add_f32_e32 v120, 1.0, v120
	v_rcp_f32_e32 v120, v120
	v_pk_mul_f32 v[124:125], v[124:125], v[140:141] op_sel_hi:[1,0]
	v_cvt_pk_bf16_f32 v115, v115, v118
	v_mul_f32_e32 v118, v122, v119
	v_mul_f32_e32 v116, v116, v118
	v_mul_f32_e32 v118, v123, v120
	v_mul_f32_e32 v119, 0xbfb8aa3b, v124
	v_mul_f32_e32 v120, 0xbfb8aa3b, v125
	v_exp_f32_e32 v119, v119
	v_exp_f32_e32 v120, v120
	v_mul_f32_e32 v117, v117, v118
	v_cvt_pk_bf16_f32 v116, v116, v117
	v_add_f32_e32 v118, 1.0, v119
	v_add_f32_e32 v119, 1.0, v120
	v_rcp_f32_e32 v118, v118
	v_rcp_f32_e32 v119, v119
	v_or_b32_e32 v136, 16, v164
	v_mad_i64_i32 v[120:121], s[2:3], v136, s71, v[130:131]
	v_mul_f32_e32 v117, v124, v118
	v_mul_f32_e32 v118, v125, v119
	v_mul_f32_e32 v117, v134, v117
	v_mul_f32_e32 v118, v135, v118
	v_cvt_pk_bf16_f32 v117, v117, v118
	ds_read_b32 v118, v165 offset:128
	v_lshl_add_u64 v[120:121], v[120:121], 0, v[132:133]
	global_store_dwordx4 v[120:121], v[114:117], off
	s_waitcnt lgkmcnt(0)
; __device__ __forceinline__ unsigned cvt_pk_bf16(float lo, float hi) { unsigned r; asm volatile("v_cvt_pk_bf16_f32 %0, %1, %2" : "=v"(r) : "v"(lo), "v"(hi)); return r; }
; __device__ __forceinline__ float silu_f(float g) { return g * __builtin_amdgcn_rcpf(1.0f + __expf(-g)); }
;     __device__ __forceinline__ void operator()(const f32x4 (&acc)[2][2][4][2], const Unit& u, int ui, int wr, int wc, int fr, int fq) const {
;     ...
;             for (int m = 0; m < 4; ++m) {
;                 const int row = row0 + ai * HALF + m * 16;
;                 const float s = rsb[(ui & 1) * 256 + ai * HALF + wr * 64 + m * 16 + fr];
;                 f32x4 g0 = acc[ai][0][m][0] * s, g1 = acc[ai][0][m][1] * s, u0 = acc[ai][1][m][0] * s, u1 = acc[ai][1][m][1] * s;
;                 u32x4 w;
;                 w.x = cvt_pk_bf16(silu_f(g0[0]) * u0[0], silu_f(g0[1]) * u0[1]); w.y = cvt_pk_bf16(silu_f(g0[2]) * u0[2], silu_f(g0[3]) * u0[3]);
;                 w.z = cvt_pk_bf16(silu_f(g1[0]) * u1[0], silu_f(g1[1]) * u1[1]); w.w = cvt_pk_bf16(silu_f(g1[2]) * u1[2], silu_f(g1[3]) * u1[3]);
;                 *(u32x4*)(H + (size_t)row * ldh + col0) = w;
	v_pk_mul_f32 v[110:111], v[110:111], v[118:119] op_sel_hi:[1,0]
	s_nop 0
	v_mul_f32_e32 v114, 0xbfb8aa3b, v110
	v_exp_f32_e32 v117, v114
	v_mul_f32_e32 v114, 0xbfb8aa3b, v111
	v_pk_mul_f32 v[112:113], v[112:113], v[118:119] op_sel_hi:[1,0]
	v_pk_mul_f32 v[108:109], v[108:109], v[118:119] op_sel_hi:[1,0]
	v_pk_mul_f32 v[106:107], v[106:107], v[118:119] op_sel_hi:[1,0]
	v_pk_mul_f32 v[104:105], v[104:105], v[118:119] op_sel_hi:[1,0]
	v_pk_mul_f32 v[102:103], v[102:103], v[118:119] op_sel_hi:[1,0]
	v_exp_f32_e32 v119, v114
	v_or_b32_e32 v116, 32, v164
	v_pk_mul_f32 v[114:115], v[100:101], v[118:119] op_sel_hi:[1,0]
	v_add_f32_e32 v100, 1.0, v117
	v_rcp_f32_e32 v117, v100
	v_add_f32_e32 v100, 1.0, v119
	v_rcp_f32_e32 v119, v100
	s_nop 0
	v_pk_mul_f32 v[100:101], v[98:99], v[118:119] op_sel_hi:[1,0]
	v_mul_f32_e32 v98, v110, v117
	v_mul_f32_e32 v98, v102, v98
	v_mul_f32_e32 v102, 0xbfb8aa3b, v112
	v_mul_f32_e32 v110, 0xbfb8aa3b, v113
	v_exp_f32_e32 v102, v102
	v_exp_f32_e32 v110, v110
	v_mul_f32_e32 v99, v111, v119
	v_mul_f32_e32 v99, v103, v99
	v_add_f32_e32 v102, 1.0, v102
	v_add_f32_e32 v103, 1.0, v110
	v_rcp_f32_e32 v102, v102
	v_rcp_f32_e32 v103, v103
	v_cvt_pk_bf16_f32 v98, v98, v99
	v_mul_f32_e32 v99, v112, v102
	v_mul_f32_e32 v102, v113, v103
	v_mul_f32_e32 v103, 0xbfb8aa3b, v106
	v_mul_f32_e32 v99, v104, v99
	v_exp_f32_e32 v103, v103
	v_mul_f32_e32 v104, 0xbfb8aa3b, v107
	v_exp_f32_e32 v104, v104
	v_mul_f32_e32 v102, v105, v102
	v_add_f32_e32 v103, 1.0, v103
	v_rcp_f32_e32 v103, v103
	v_add_f32_e32 v104, 1.0, v104
	v_rcp_f32_e32 v104, v104
	v_cvt_pk_bf16_f32 v99, v99, v102
	v_mul_f32_e32 v102, v106, v103
	v_mul_f32_e32 v100, v100, v102
	v_mul_f32_e32 v102, v107, v104
	v_mul_f32_e32 v103, 0xbfb8aa3b, v108
	v_mul_f32_e32 v104, 0xbfb8aa3b, v109
	v_exp_f32_e32 v103, v103
	v_exp_f32_e32 v104, v104
	v_mul_f32_e32 v101, v101, v102
	v_cvt_pk_bf16_f32 v100, v100, v101
	v_add_f32_e32 v102, 1.0, v103
	v_add_f32_e32 v103, 1.0, v104
	v_rcp_f32_e32 v102, v102
	v_rcp_f32_e32 v103, v103
	v_mad_i64_i32 v[104:105], s[2:3], v116, s71, v[130:131]
	v_mul_f32_e32 v101, v108, v102
	v_mul_f32_e32 v102, v109, v103
	v_mul_f32_e32 v101, v114, v101
	v_mul_f32_e32 v102, v115, v102
	v_cvt_pk_bf16_f32 v101, v101, v102
	ds_read_b32 v102, v165 offset:192
	v_lshl_add_u64 v[104:105], v[104:105], 0, v[132:133]
	global_store_dwordx4 v[104:105], v[98:101], off
	s_waitcnt lgkmcnt(0)
	v_pk_mul_f32 v[94:95], v[94:95], v[102:103] op_sel_hi:[1,0]
	s_nop 0
	v_mul_f32_e32 v98, 0xbfb8aa3b, v94
	v_exp_f32_e32 v101, v98
	v_mul_f32_e32 v98, 0xbfb8aa3b, v95
	v_pk_mul_f32 v[96:97], v[96:97], v[102:103] op_sel_hi:[1,0]
	v_pk_mul_f32 v[92:93], v[92:93], v[102:103] op_sel_hi:[1,0]
	v_pk_mul_f32 v[90:91], v[90:91], v[102:103] op_sel_hi:[1,0]
	v_pk_mul_f32 v[88:89], v[88:89], v[102:103] op_sel_hi:[1,0]
	v_pk_mul_f32 v[86:87], v[86:87], v[102:103] op_sel_hi:[1,0]
	v_exp_f32_e32 v103, v98
	v_or_b32_e32 v100, 48, v164
	v_pk_mul_f32 v[98:99], v[84:85], v[102:103] op_sel_hi:[1,0]
	v_add_f32_e32 v84, 1.0, v101
	v_rcp_f32_e32 v101, v84
	v_add_f32_e32 v84, 1.0, v103
	v_rcp_f32_e32 v103, v84
	s_nop 0
	v_pk_mul_f32 v[84:85], v[82:83], v[102:103] op_sel_hi:[1,0]
	v_mul_f32_e32 v82, v94, v101
	v_mul_f32_e32 v82, v86, v82
	v_mul_f32_e32 v86, 0xbfb8aa3b, v96
	v_mul_f32_e32 v94, 0xbfb8aa3b, v97
	v_exp_f32_e32 v86, v86
	v_exp_f32_e32 v94, v94
	v_mul_f32_e32 v83, v95, v103
	v_mul_f32_e32 v83, v87, v83
	v_add_f32_e32 v86, 1.0, v86
	v_add_f32_e32 v87, 1.0, v94
	v_rcp_f32_e32 v86, v86
	v_rcp_f32_e32 v87, v87
	v_cvt_pk_bf16_f32 v82, v82, v83
	v_mul_f32_e32 v83, v96, v86
	v_mul_f32_e32 v86, v97, v87
	v_mul_f32_e32 v87, 0xbfb8aa3b, v90
	v_mul_f32_e32 v83, v88, v83
	v_exp_f32_e32 v87, v87
	v_mul_f32_e32 v88, 0xbfb8aa3b, v91
	v_exp_f32_e32 v88, v88
	v_mul_f32_e32 v86, v89, v86
	v_add_f32_e32 v87, 1.0, v87
	v_rcp_f32_e32 v87, v87
	v_add_f32_e32 v88, 1.0, v88
	v_rcp_f32_e32 v88, v88
	v_cvt_pk_bf16_f32 v83, v83, v86
	v_mul_f32_e32 v86, v90, v87
	v_mul_f32_e32 v84, v84, v86
	v_mul_f32_e32 v86, v91, v88
	v_mul_f32_e32 v87, 0xbfb8aa3b, v92
	v_mul_f32_e32 v88, 0xbfb8aa3b, v93
	v_exp_f32_e32 v87, v87
	v_exp_f32_e32 v88, v88
	v_mul_f32_e32 v85, v85, v86
	v_cvt_pk_bf16_f32 v84, v84, v85
	v_add_f32_e32 v86, 1.0, v87
	v_add_f32_e32 v87, 1.0, v88
	v_rcp_f32_e32 v86, v86
	v_rcp_f32_e32 v87, v87
	v_mad_i64_i32 v[88:89], s[2:3], v100, s71, v[130:131]
	v_mul_f32_e32 v85, v92, v86
	v_mul_f32_e32 v86, v93, v87
	v_mul_f32_e32 v85, v98, v85
	v_mul_f32_e32 v86, v99, v86
	v_cvt_pk_bf16_f32 v85, v85, v86
	ds_read_b32 v86, v165 offset:512
	v_lshl_add_u64 v[88:89], v[88:89], 0, v[132:133]
	global_store_dwordx4 v[88:89], v[82:85], off
	s_waitcnt lgkmcnt(0)
; __device__ __forceinline__ unsigned cvt_pk_bf16(float lo, float hi) { unsigned r; asm volatile("v_cvt_pk_bf16_f32 %0, %1, %2" : "=v"(r) : "v"(lo), "v"(hi)); return r; }
; __device__ __forceinline__ float silu_f(float g) { return g * __builtin_amdgcn_rcpf(1.0f + __expf(-g)); }
;     __device__ __forceinline__ void operator()(const f32x4 (&acc)[2][2][4][2], const Unit& u, int ui, int wr, int wc, int fr, int fq) const {
;     ...
;             for (int m = 0; m < 4; ++m) {
;                 const int row = row0 + ai * HALF + m * 16;
;                 const float s = rsb[(ui & 1) * 256 + ai * HALF + wr * 64 + m * 16 + fr];
;                 f32x4 g0 = acc[ai][0][m][0] * s, g1 = acc[ai][0][m][1] * s, u0 = acc[ai][1][m][0] * s, u1 = acc[ai][1][m][1] * s;
;                 u32x4 w;
;                 w.x = cvt_pk_bf16(silu_f(g0[0]) * u0[0], silu_f(g0[1]) * u0[1]); w.y = cvt_pk_bf16(silu_f(g0[2]) * u0[2], silu_f(g0[3]) * u0[3]);
;                 w.z = cvt_pk_bf16(silu_f(g1[0]) * u1[0], silu_f(g1[1]) * u1[1]); w.w = cvt_pk_bf16(silu_f(g1[2]) * u1[2], silu_f(g1[3]) * u1[3]);
;                 *(u32x4*)(H + (size_t)row * ldh + col0) = w;
	v_pk_mul_f32 v[78:79], v[78:79], v[86:87] op_sel_hi:[1,0]
	s_nop 0
	v_mul_f32_e32 v82, 0xbfb8aa3b, v78
	v_exp_f32_e32 v85, v82
	v_mul_f32_e32 v82, 0xbfb8aa3b, v79
	v_pk_mul_f32 v[80:81], v[80:81], v[86:87] op_sel_hi:[1,0]
	v_pk_mul_f32 v[76:77], v[76:77], v[86:87] op_sel_hi:[1,0]
	v_pk_mul_f32 v[74:75], v[74:75], v[86:87] op_sel_hi:[1,0]
	v_pk_mul_f32 v[72:73], v[72:73], v[86:87] op_sel_hi:[1,0]
	v_pk_mul_f32 v[70:71], v[70:71], v[86:87] op_sel_hi:[1,0]
	v_exp_f32_e32 v87, v82
	v_add_u32_e32 v84, 0x80, v164
	v_pk_mul_f32 v[82:83], v[68:69], v[86:87] op_sel_hi:[1,0]
	v_add_f32_e32 v68, 1.0, v85
	v_rcp_f32_e32 v85, v68
	v_add_f32_e32 v68, 1.0, v87
	v_rcp_f32_e32 v87, v68
	s_nop 0
	v_pk_mul_f32 v[68:69], v[66:67], v[86:87] op_sel_hi:[1,0]
	v_mul_f32_e32 v66, v78, v85
	v_mul_f32_e32 v66, v70, v66
	v_mul_f32_e32 v70, 0xbfb8aa3b, v80
	v_mul_f32_e32 v78, 0xbfb8aa3b, v81
	v_exp_f32_e32 v70, v70
	v_exp_f32_e32 v78, v78
	v_mul_f32_e32 v67, v79, v87
	v_mul_f32_e32 v67, v71, v67
	v_add_f32_e32 v70, 1.0, v70
	v_add_f32_e32 v71, 1.0, v78
	v_rcp_f32_e32 v70, v70
	v_rcp_f32_e32 v71, v71
	v_cvt_pk_bf16_f32 v66, v66, v67
	v_mul_f32_e32 v67, v80, v70
	v_mul_f32_e32 v70, v81, v71
	v_mul_f32_e32 v71, 0xbfb8aa3b, v74
	v_mul_f32_e32 v67, v72, v67
	v_exp_f32_e32 v71, v71
	v_mul_f32_e32 v72, 0xbfb8aa3b, v75
	v_exp_f32_e32 v72, v72
	v_mul_f32_e32 v70, v73, v70
	v_add_f32_e32 v71, 1.0, v71
	v_rcp_f32_e32 v71, v71
	v_add_f32_e32 v72, 1.0, v72
	v_rcp_f32_e32 v72, v72
	v_cvt_pk_bf16_f32 v67, v67, v70
	v_mul_f32_e32 v70, v74, v71
	v_mul_f32_e32 v68, v68, v70
	v_mul_f32_e32 v70, v75, v72
	v_mul_f32_e32 v71, 0xbfb8aa3b, v76
	v_mul_f32_e32 v72, 0xbfb8aa3b, v77
	v_exp_f32_e32 v71, v71
	v_exp_f32_e32 v72, v72
	v_mul_f32_e32 v69, v69, v70
	v_cvt_pk_bf16_f32 v68, v68, v69
	v_add_f32_e32 v70, 1.0, v71
	v_add_f32_e32 v71, 1.0, v72
	v_rcp_f32_e32 v70, v70
	v_rcp_f32_e32 v71, v71
	v_mad_i64_i32 v[72:73], s[2:3], v84, s71, v[130:131]
	v_mul_f32_e32 v69, v76, v70
	v_mul_f32_e32 v70, v77, v71
	v_mul_f32_e32 v69, v82, v69
	v_mul_f32_e32 v70, v83, v70
	v_cvt_pk_bf16_f32 v69, v69, v70
	ds_read_b32 v70, v165 offset:576
	v_lshl_add_u64 v[72:73], v[72:73], 0, v[132:133]
	global_store_dwordx4 v[72:73], v[66:69], off
	s_waitcnt lgkmcnt(0)
	v_pk_mul_f32 v[62:63], v[62:63], v[70:71] op_sel_hi:[1,0]
	s_nop 0
	v_mul_f32_e32 v66, 0xbfb8aa3b, v62
	v_exp_f32_e32 v69, v66
	v_mul_f32_e32 v66, 0xbfb8aa3b, v63
	v_pk_mul_f32 v[64:65], v[64:65], v[70:71] op_sel_hi:[1,0]
	v_pk_mul_f32 v[60:61], v[60:61], v[70:71] op_sel_hi:[1,0]
	v_pk_mul_f32 v[58:59], v[58:59], v[70:71] op_sel_hi:[1,0]
	v_pk_mul_f32 v[56:57], v[56:57], v[70:71] op_sel_hi:[1,0]
	v_pk_mul_f32 v[54:55], v[54:55], v[70:71] op_sel_hi:[1,0]
	v_exp_f32_e32 v71, v66
	v_add_u32_e32 v68, 0x90, v164
	v_pk_mul_f32 v[66:67], v[52:53], v[70:71] op_sel_hi:[1,0]
	v_add_f32_e32 v52, 1.0, v69
	v_rcp_f32_e32 v69, v52
	v_add_f32_e32 v52, 1.0, v71
	v_rcp_f32_e32 v71, v52
	s_nop 0
	v_pk_mul_f32 v[52:53], v[50:51], v[70:71] op_sel_hi:[1,0]
	v_mul_f32_e32 v50, v62, v69
	v_mul_f32_e32 v50, v54, v50
	v_mul_f32_e32 v54, 0xbfb8aa3b, v64
	v_mul_f32_e32 v62, 0xbfb8aa3b, v65
	v_exp_f32_e32 v54, v54
	v_exp_f32_e32 v62, v62
	v_mul_f32_e32 v51, v63, v71
	v_mul_f32_e32 v51, v55, v51
	v_add_f32_e32 v54, 1.0, v54
	v_add_f32_e32 v55, 1.0, v62
	v_rcp_f32_e32 v54, v54
	v_rcp_f32_e32 v55, v55
	v_cvt_pk_bf16_f32 v50, v50, v51
	v_mul_f32_e32 v51, v64, v54
	v_mul_f32_e32 v54, v65, v55
	v_mul_f32_e32 v55, 0xbfb8aa3b, v58
	v_mul_f32_e32 v51, v56, v51
	v_exp_f32_e32 v55, v55
	v_mul_f32_e32 v56, 0xbfb8aa3b, v59
	v_exp_f32_e32 v56, v56
	v_mul_f32_e32 v54, v57, v54
	v_add_f32_e32 v55, 1.0, v55
	v_rcp_f32_e32 v55, v55
	v_add_f32_e32 v56, 1.0, v56
	v_rcp_f32_e32 v56, v56
	v_cvt_pk_bf16_f32 v51, v51, v54
	v_mul_f32_e32 v54, v58, v55
	v_mul_f32_e32 v52, v52, v54
	v_mul_f32_e32 v54, v59, v56
	v_mul_f32_e32 v55, 0xbfb8aa3b, v60
	v_mul_f32_e32 v56, 0xbfb8aa3b, v61
	v_exp_f32_e32 v55, v55
	v_exp_f32_e32 v56, v56
	v_mul_f32_e32 v53, v53, v54
	v_cvt_pk_bf16_f32 v52, v52, v53
	v_add_f32_e32 v54, 1.0, v55
	v_add_f32_e32 v55, 1.0, v56
	v_rcp_f32_e32 v54, v54
	v_rcp_f32_e32 v55, v55
	v_mad_i64_i32 v[56:57], s[2:3], v68, s71, v[130:131]
	v_mul_f32_e32 v53, v60, v54
	v_mul_f32_e32 v54, v61, v55
	v_mul_f32_e32 v53, v66, v53
	v_mul_f32_e32 v54, v67, v54
	v_cvt_pk_bf16_f32 v53, v53, v54
	ds_read_b32 v54, v165 offset:640
	v_lshl_add_u64 v[56:57], v[56:57], 0, v[132:133]
	global_store_dwordx4 v[56:57], v[50:53], off
	s_waitcnt lgkmcnt(0)
; __device__ __forceinline__ unsigned cvt_pk_bf16(float lo, float hi) { unsigned r; asm volatile("v_cvt_pk_bf16_f32 %0, %1, %2" : "=v"(r) : "v"(lo), "v"(hi)); return r; }
; __device__ __forceinline__ float silu_f(float g) { return g * __builtin_amdgcn_rcpf(1.0f + __expf(-g)); }
;     static __device__ __forceinline__ float fin(const f32x4& a, const f32x4& b, const f32x4& c, const f32x4& d) {
;         const float s = (((a[0] + a[1]) + (a[2] + a[3])) + ((b[0] + b[1]) + (b[2] + b[3]))) + (((c[0] + c[1]) + (c[2] + c[3])) + ((d[0] + d[1]) + (d[2] + d[3])));
;         return 1.0f / sqrtf(s * (1.0f / 1024.0f) + 1e-6f); }
;     __device__ __forceinline__ void issue(const Unit& u, Pre& p) const {
;         int t = threadIdx.x; asm volatile("" : "+v"(t));
;         if (t < 256) { gp_t g = (gp_t)(ssq + (size_t)(u.pm * BM + t) * 16); p.a = g[0]; p.b = g[1]; p.c = g[2]; p.d = g[3]; }
;     }
;     __device__ __forceinline__ void commit(const Unit& u, int ui, const Pre& p) const {
;         int t = threadIdx.x; asm volatile("" : "+v"(t));
;         if (t < 256) rsb[(ui & 1) * 256 + t] = fin(p.a, p.b, p.c, p.d);
;     }
;     __device__ __forceinline__ void operator()(const f32x4 (&acc)[2][2][4][2], const Unit& u, int ui, int wr, int wc, int fr, int fq) const {
;     ...
;             for (int m = 0; m < 4; ++m) {
;                 const int row = row0 + ai * HALF + m * 16;
;                 const float s = rsb[(ui & 1) * 256 + ai * HALF + wr * 64 + m * 16 + fr];
;                 f32x4 g0 = acc[ai][0][m][0] * s, g1 = acc[ai][0][m][1] * s, u0 = acc[ai][1][m][0] * s, u1 = acc[ai][1][m][1] * s;
;                 u32x4 w;
;                 w.x = cvt_pk_bf16(silu_f(g0[0]) * u0[0], silu_f(g0[1]) * u0[1]); w.y = cvt_pk_bf16(silu_f(g0[2]) * u0[2], silu_f(g0[3]) * u0[3]);
;                 w.z = cvt_pk_bf16(silu_f(g1[0]) * u1[0], silu_f(g1[1]) * u1[1]); w.w = cvt_pk_bf16(silu_f(g1[2]) * u1[2], silu_f(g1[3]) * u1[3]);
;                 *(u32x4*)(H + (size_t)row * ldh + col0) = w;
	v_pk_mul_f32 v[46:47], v[46:47], v[54:55] op_sel_hi:[1,0]
	s_nop 0
	v_mul_f32_e32 v50, 0xbfb8aa3b, v46
	v_exp_f32_e32 v53, v50
	v_mul_f32_e32 v50, 0xbfb8aa3b, v47
	v_pk_mul_f32 v[48:49], v[48:49], v[54:55] op_sel_hi:[1,0]
	v_pk_mul_f32 v[44:45], v[44:45], v[54:55] op_sel_hi:[1,0]
	v_pk_mul_f32 v[42:43], v[42:43], v[54:55] op_sel_hi:[1,0]
	v_pk_mul_f32 v[40:41], v[40:41], v[54:55] op_sel_hi:[1,0]
	v_pk_mul_f32 v[38:39], v[38:39], v[54:55] op_sel_hi:[1,0]
	v_exp_f32_e32 v55, v50
	v_add_u32_e32 v52, 0xa0, v164
	v_pk_mul_f32 v[50:51], v[36:37], v[54:55] op_sel_hi:[1,0]
	v_add_f32_e32 v36, 1.0, v53
	v_rcp_f32_e32 v53, v36
	v_add_f32_e32 v36, 1.0, v55
	v_rcp_f32_e32 v55, v36
	s_nop 0
	v_pk_mul_f32 v[36:37], v[34:35], v[54:55] op_sel_hi:[1,0]
	v_mul_f32_e32 v34, v46, v53
	v_mul_f32_e32 v34, v38, v34
	v_mul_f32_e32 v38, 0xbfb8aa3b, v48
	v_mul_f32_e32 v46, 0xbfb8aa3b, v49
	v_exp_f32_e32 v38, v38
	v_exp_f32_e32 v46, v46
	v_mul_f32_e32 v35, v47, v55
	v_mul_f32_e32 v35, v39, v35
	v_add_f32_e32 v38, 1.0, v38
	v_add_f32_e32 v39, 1.0, v46
	v_rcp_f32_e32 v38, v38
	v_rcp_f32_e32 v39, v39
	v_cvt_pk_bf16_f32 v34, v34, v35
	v_mul_f32_e32 v35, v48, v38
	v_mul_f32_e32 v38, v49, v39
	v_mul_f32_e32 v39, 0xbfb8aa3b, v42
	v_mul_f32_e32 v35, v40, v35
	v_exp_f32_e32 v39, v39
	v_mul_f32_e32 v40, 0xbfb8aa3b, v43
	v_exp_f32_e32 v40, v40
	v_mul_f32_e32 v38, v41, v38
	v_add_f32_e32 v39, 1.0, v39
	v_rcp_f32_e32 v39, v39
	v_add_f32_e32 v40, 1.0, v40
	v_rcp_f32_e32 v40, v40
	v_cvt_pk_bf16_f32 v35, v35, v38
	v_mul_f32_e32 v38, v42, v39
	v_mul_f32_e32 v36, v36, v38
	v_mul_f32_e32 v38, v43, v40
	v_mul_f32_e32 v39, 0xbfb8aa3b, v44
	v_mul_f32_e32 v40, 0xbfb8aa3b, v45
	v_exp_f32_e32 v39, v39
	v_exp_f32_e32 v40, v40
	v_mul_f32_e32 v37, v37, v38
	v_cvt_pk_bf16_f32 v36, v36, v37
	v_add_f32_e32 v38, 1.0, v39
	v_add_f32_e32 v39, 1.0, v40
	v_rcp_f32_e32 v38, v38
	v_rcp_f32_e32 v39, v39
	v_mad_i64_i32 v[40:41], s[2:3], v52, s71, v[130:131]
	v_mul_f32_e32 v37, v44, v38
	v_mul_f32_e32 v38, v45, v39
	v_mul_f32_e32 v37, v50, v37
	v_mul_f32_e32 v38, v51, v38
	v_cvt_pk_bf16_f32 v37, v37, v38
	ds_read_b32 v38, v165 offset:704
	v_lshl_add_u64 v[40:41], v[40:41], 0, v[132:133]
	global_store_dwordx4 v[40:41], v[34:37], off
	s_waitcnt lgkmcnt(0)
	v_pk_mul_f32 v[30:31], v[30:31], v[38:39] op_sel_hi:[1,0]
	s_nop 0
	v_mul_f32_e32 v34, 0xbfb8aa3b, v30
	v_exp_f32_e32 v37, v34
	v_mul_f32_e32 v34, 0xbfb8aa3b, v31
	v_pk_mul_f32 v[32:33], v[32:33], v[38:39] op_sel_hi:[1,0]
	v_pk_mul_f32 v[28:29], v[28:29], v[38:39] op_sel_hi:[1,0]
	v_pk_mul_f32 v[26:27], v[26:27], v[38:39] op_sel_hi:[1,0]
	v_pk_mul_f32 v[24:25], v[24:25], v[38:39] op_sel_hi:[1,0]
	v_pk_mul_f32 v[22:23], v[22:23], v[38:39] op_sel_hi:[1,0]
	v_exp_f32_e32 v39, v34
	v_add_u32_e32 v36, 0xb0, v164
	v_pk_mul_f32 v[34:35], v[20:21], v[38:39] op_sel_hi:[1,0]
	v_add_f32_e32 v20, 1.0, v37
	v_rcp_f32_e32 v37, v20
	v_add_f32_e32 v20, 1.0, v39
	v_rcp_f32_e32 v39, v20
	s_nop 0
	v_pk_mul_f32 v[20:21], v[18:19], v[38:39] op_sel_hi:[1,0]
	v_mul_f32_e32 v18, v30, v37
	v_mul_f32_e32 v18, v22, v18
	v_mul_f32_e32 v22, 0xbfb8aa3b, v32
	v_mul_f32_e32 v30, 0xbfb8aa3b, v33
	v_exp_f32_e32 v22, v22
	v_exp_f32_e32 v30, v30
	v_mul_f32_e32 v19, v31, v39
	v_mul_f32_e32 v19, v23, v19
	v_add_f32_e32 v22, 1.0, v22
	v_add_f32_e32 v23, 1.0, v30
	v_rcp_f32_e32 v22, v22
	v_rcp_f32_e32 v23, v23
	v_cvt_pk_bf16_f32 v18, v18, v19
	v_mul_f32_e32 v19, v32, v22
	v_mul_f32_e32 v22, v33, v23
	v_mul_f32_e32 v23, 0xbfb8aa3b, v26
	v_mul_f32_e32 v19, v24, v19
	v_exp_f32_e32 v23, v23
	v_mul_f32_e32 v24, 0xbfb8aa3b, v27
	v_exp_f32_e32 v24, v24
	v_mul_f32_e32 v22, v25, v22
	v_add_f32_e32 v23, 1.0, v23
	v_rcp_f32_e32 v23, v23
	v_add_f32_e32 v24, 1.0, v24
	v_rcp_f32_e32 v24, v24
	v_cvt_pk_bf16_f32 v19, v19, v22
	v_mul_f32_e32 v22, v26, v23
	v_mul_f32_e32 v20, v20, v22
	v_mul_f32_e32 v22, v27, v24
	v_mul_f32_e32 v23, 0xbfb8aa3b, v28
	v_mul_f32_e32 v24, 0xbfb8aa3b, v29
	v_exp_f32_e32 v23, v23
	v_exp_f32_e32 v24, v24
	v_mul_f32_e32 v21, v21, v22
	v_cvt_pk_bf16_f32 v20, v20, v21
	v_add_f32_e32 v22, 1.0, v23
	v_add_f32_e32 v23, 1.0, v24
	v_rcp_f32_e32 v22, v22
	v_rcp_f32_e32 v23, v23
	v_mul_f32_e32 v21, v28, v22
	v_mul_f32_e32 v22, v29, v23
	v_mul_f32_e32 v21, v34, v21
	v_mul_f32_e32 v22, v35, v22
	v_cvt_pk_bf16_f32 v21, v21, v22
	v_mad_i64_i32 v[22:23], s[2:3], v36, s71, v[130:131]
	v_lshl_add_u64 v[22:23], v[22:23], 0, v[132:133]
	s_mov_b64 s[2:3], -1
	global_store_dwordx4 v[22:23], v[18:21], off
	s_cbranch_scc1 .LBB0_117
	s_nop 0
	v_mov_b32_e32 v18, v204
	s_nop 0
	v_cmp_gt_i32_e32 vcc, s68, v18
	s_and_saveexec_b64 s[20:21], vcc
	s_cbranch_execz .LBB0_131
	s_waitcnt vmcnt(8)
	v_mov_b32_e32 v20, v6
	v_mov_b32_e32 v21, v14
	v_mov_b32_e32 v22, v7
	v_mov_b32_e32 v23, v15
	v_pk_add_f32 v[20:21], v[20:21], v[22:23]
	v_mov_b32_e32 v22, v8
	v_mov_b32_e32 v23, v16
	v_mov_b32_e32 v24, v9
	v_mov_b32_e32 v25, v17
	v_pk_add_f32 v[22:23], v[22:23], v[24:25]
	v_mov_b32_e32 v24, v3
	v_pk_add_f32 v[20:21], v[20:21], v[22:23]
	v_mov_b32_e32 v22, v2
	v_mov_b32_e32 v23, v10
	v_mov_b32_e32 v25, v11
	v_pk_add_f32 v[22:23], v[22:23], v[24:25]
	v_mov_b32_e32 v24, v4
	v_mov_b32_e32 v25, v12
	v_mov_b32_e32 v26, v5
	v_mov_b32_e32 v27, v13
	v_pk_add_f32 v[24:25], v[24:25], v[26:27]
	s_nop 0
	v_pk_add_f32 v[22:23], v[22:23], v[24:25]
	s_nop 0
	v_pk_add_f32 v[20:21], v[22:23], v[20:21]
	s_nop 0
	v_add_f32_e32 v19, v20, v21
	v_fmamk_f32 v19, v19, 0x3a800000, v205
	v_mul_f32_e32 v20, 0x4f800000, v19
	v_cmp_gt_f32_e32 vcc, s69, v19
	s_nop 1
	v_cndmask_b32_e32 v19, v19, v20, vcc
	v_sqrt_f32_e32 v20, v19
	s_nop 0
	v_add_u32_e32 v21, -1, v20
	v_fma_f32 v22, -v21, v20, v19
	v_cmp_ge_f32_e64 s[2:3], 0, v22
	v_add_u32_e32 v22, 1, v20
	s_nop 0
	v_cndmask_b32_e64 v21, v20, v21, s[2:3]
	v_fma_f32 v20, -v22, v20, v19
	v_cmp_lt_f32_e64 s[2:3], 0, v20
	s_nop 1
	v_cndmask_b32_e64 v20, v21, v22, s[2:3]
	v_mul_f32_e32 v21, 0x37800000, v20
	v_cndmask_b32_e32 v20, v20, v21, vcc
	v_cmp_class_f32_e32 vcc, v19, v206
	s_nop 1
	v_cndmask_b32_e32 v19, v20, v19, vcc
	v_div_scale_f32 v20, s[2:3], v19, v19, 1.0
	v_rcp_f32_e32 v21, v20
	s_lshl_b32 s2, s60, 10
	s_and_b32 s2, s2, 0x400
	s_add_i32 s2, s2, 0
	v_fma_f32 v22, -v20, v21, 1.0
	v_fmac_f32_e32 v21, v22, v21
	v_div_scale_f32 v22, vcc, 1.0, v19, 1.0
	v_mul_f32_e32 v23, v22, v21
	v_fma_f32 v24, -v20, v23, v22
	v_fmac_f32_e32 v23, v24, v21
	v_fma_f32 v20, -v20, v23, v22
	v_div_fmas_f32 v20, v20, v21, v23
	v_lshl_add_u32 v18, v18, 2, s2
	v_div_fixup_f32 v19, v20, v19, 1.0
	v_add_u32_e32 v18, 0x20400, v18
	ds_write_b32 v18, v19

;     __device__ __forceinline__ void issue(const Unit& u, Pre& p) const {
;         int t = threadIdx.x; asm volatile("" : "+v"(t));
;         if (t < 256) { gp_t g = (gp_t)(ssq + (size_t)(u.pm * BM + t) * 16); p.a = g[0]; p.b = g[1]; p.c = g[2]; p.d = g[3]; }
;     }
.LBB0_322:
	s_andn2_b64 vcc, exec, s[2:3]
	s_cbranch_vccnz .LBB0_326
	v_mov_b32_e32 v146, v204
	s_nop 0
	v_cmp_gt_i32_e32 vcc, s68, v146
	s_and_saveexec_b64 s[2:3], vcc
	s_cbranch_execz .LBB0_325
	s_nop 0
	v_lshl_add_u32 v2, s16, 8, v146
	v_ashrrev_i32_e32 v3, 31, v2
	v_lshlrev_b64 v[2:3], 6, v[2:3]
	v_lshl_add_u64 v[14:15], s[4:5], 0, v[2:3]
	global_load_dwordx4 v[2:5], v[14:15], off offset:48
	global_load_dwordx4 v[6:9], v[14:15], off offset:32
	global_load_dwordx4 v[10:13], v[14:15], off offset:16
	s_nop 0
	global_load_dwordx4 v[14:17], v[14:15], off

;     __device__ __forceinline__ void commit(const Unit& u, int ui, const Pre& p) const {
;         int t = threadIdx.x; asm volatile("" : "+v"(t));
;         if (t < 256) rsb[(ui & 1) * 256 + t] = fin(p.a, p.b, p.c, p.d);
;     }
.LBB0_331:
	v_mov_b32_e32 v18, v204
	s_nop 0
	v_cmp_gt_i32_e32 vcc, s68, v18
	s_and_saveexec_b64 s[24:25], vcc
	s_cbranch_execz .LBB0_333
	s_waitcnt vmcnt(16)
	v_mov_b32_e32 v20, v6
	v_mov_b32_e32 v21, v14
	v_mov_b32_e32 v22, v7
	v_mov_b32_e32 v23, v15
	v_pk_add_f32 v[20:21], v[20:21], v[22:23]
	v_mov_b32_e32 v22, v8
	v_mov_b32_e32 v23, v16
	v_mov_b32_e32 v24, v9
	v_mov_b32_e32 v25, v17
	v_pk_add_f32 v[22:23], v[22:23], v[24:25]
	v_mov_b32_e32 v24, v3
	v_pk_add_f32 v[20:21], v[20:21], v[22:23]
	v_mov_b32_e32 v22, v2
	v_mov_b32_e32 v23, v10
	v_mov_b32_e32 v25, v11
	v_pk_add_f32 v[22:23], v[22:23], v[24:25]
	v_mov_b32_e32 v24, v4
	v_mov_b32_e32 v25, v12
	v_mov_b32_e32 v26, v5
	v_mov_b32_e32 v27, v13
	v_pk_add_f32 v[24:25], v[24:25], v[26:27]
	s_nop 0
	v_pk_add_f32 v[22:23], v[22:23], v[24:25]
	s_nop 0
	v_pk_add_f32 v[20:21], v[22:23], v[20:21]
	s_nop 0
	v_add_f32_e32 v19, v20, v21
	v_fmamk_f32 v19, v19, 0x3a800000, v205
	v_mul_f32_e32 v20, 0x4f800000, v19
	v_cmp_gt_f32_e32 vcc, s69, v19
	s_nop 1
	v_cndmask_b32_e32 v19, v19, v20, vcc
	v_sqrt_f32_e32 v20, v19
	s_nop 0
	v_add_u32_e32 v21, -1, v20
	v_fma_f32 v22, -v21, v20, v19
	v_cmp_ge_f32_e64 s[2:3], 0, v22
	v_add_u32_e32 v22, 1, v20
	s_nop 0
	v_cndmask_b32_e64 v21, v20, v21, s[2:3]
	v_fma_f32 v20, -v22, v20, v19
	v_cmp_lt_f32_e64 s[2:3], 0, v20
	s_nop 1
	v_cndmask_b32_e64 v20, v21, v22, s[2:3]
	v_mul_f32_e32 v21, 0x37800000, v20
	v_cndmask_b32_e32 v20, v20, v21, vcc
	v_cmp_class_f32_e32 vcc, v19, v206
	s_nop 1
	v_cndmask_b32_e32 v19, v20, v19, vcc
	v_div_scale_f32 v20, s[2:3], v19, v19, 1.0
	v_rcp_f32_e32 v21, v20
	s_lshl_b32 s2, s65, 10
	s_and_b32 s2, s2, 0x400
	s_add_i32 s2, s2, 0
	v_fma_f32 v22, -v20, v21, 1.0
	v_fmac_f32_e32 v21, v22, v21
	v_div_scale_f32 v22, vcc, 1.0, v19, 1.0
	v_mul_f32_e32 v23, v22, v21
	v_fma_f32 v24, -v20, v23, v22
	v_fmac_f32_e32 v23, v24, v21
	v_fma_f32 v20, -v20, v23, v22
	v_div_fmas_f32 v20, v20, v21, v23
	v_lshl_add_u32 v18, v18, 2, s2
	v_div_fixup_f32 v19, v20, v19, 1.0
	v_add_u32_e32 v18, 0x20400, v18
	ds_write_b32 v18, v19

; __device__ __forceinline__ unsigned f2bf(float f) { unsigned u = __builtin_bit_cast(unsigned, f); return (u + 0x7fffu + ((u >> 16) & 1u)) >> 16; }
; __device__ __forceinline__ unsigned pk2(float lo, float hi) { return f2bf(lo) | (f2bf(hi) << 16); }
; __device__ __forceinline__ void rglru_unit(LAS unsigned char* lds, int unit, const bf16* PBp, bf16* MGp, float* SSQRp, const float* cw, const float* cbias, const float* wa, const float* ba, const float* wx, const float* bxp, const float* lam) {
;     ...
;     rg_bf16x8 wb[4][2];
; #pragma unroll
;     for (int nb = 0; nb < 4; ++nb)
; #pragma unroll
;         for (int kk = 0; kk < 2; ++kk) { const float* wsrc = ((nb >> 1) ? wx : wa) + ((size_t)g * 64 + 32 * kk + 8 * fq) * 64 + hf * 32 + 16 * (nb & 1) + fr;
;             unsigned pk[4];
; #pragma unroll
;             for (int e = 0; e < 4; ++e) pk[e] = pk2(wsrc[(2 * e) * 64], wsrc[(2 * e + 1) * 64]);
;             wb[nb][kk] = __builtin_bit_cast(rg_bf16x8, (v4u){pk[0], pk[1], pk[2], pk[3]}); }
.LBB0_432:
	s_or_b64 exec, exec, s[2:3]
	v_bfe_u32 v1, v23, 16, 1
	v_add3_u32 v1, v23, v1, s84
	v_bfe_u32 v3, v20, 16, 1
	v_lshrrev_b32_e32 v1, 16, v1
	v_add3_u32 v3, v20, v3, s84
	v_and_or_b32 v20, v3, s80, v1
	v_bfe_u32 v1, v22, 16, 1
	v_add3_u32 v1, v22, v1, s84
	v_bfe_u32 v3, v21, 16, 1
	v_lshrrev_b32_e32 v1, 16, v1
	v_add3_u32 v3, v21, v3, s84
	v_and_or_b32 v21, v3, s80, v1
	v_bfe_u32 v1, v35, 16, 1
	v_add3_u32 v1, v35, v1, s84
	v_bfe_u32 v3, v34, 16, 1
	v_lshrrev_b32_e32 v1, 16, v1
	v_add3_u32 v3, v34, v3, s84
	v_and_or_b32 v22, v3, s80, v1
	v_bfe_u32 v1, v33, 16, 1
	v_add3_u32 v1, v33, v1, s84
	v_bfe_u32 v3, v32, 16, 1
	v_lshrrev_b32_e32 v1, 16, v1
	v_add3_u32 v3, v32, v3, s84
	v_and_or_b32 v23, v3, s80, v1
	v_bfe_u32 v1, v65, 16, 1
	v_add3_u32 v1, v65, v1, s84
	v_bfe_u32 v3, v63, 16, 1
	v_lshrrev_b32_e32 v1, 16, v1
	v_add3_u32 v3, v63, v3, s84
	v_and_or_b32 v32, v3, s80, v1
	v_bfe_u32 v1, v62, 16, 1
	v_add3_u32 v1, v62, v1, s84
	v_bfe_u32 v3, v60, 16, 1
	v_lshrrev_b32_e32 v1, 16, v1
	v_add3_u32 v3, v60, v3, s84
	v_and_or_b32 v33, v3, s80, v1
	v_bfe_u32 v1, v80, 16, 1
	v_add3_u32 v1, v80, v1, s84
	v_bfe_u32 v3, v78, 16, 1
	v_lshrrev_b32_e32 v1, 16, v1
	v_add3_u32 v3, v78, v3, s84
	v_and_or_b32 v34, v3, s80, v1
	v_bfe_u32 v1, v76, 16, 1
	v_add3_u32 v1, v76, v1, s84
	v_bfe_u32 v3, v70, 16, 1
	v_lshrrev_b32_e32 v1, 16, v1
	v_add3_u32 v3, v70, v3, s84
	v_and_or_b32 v35, v3, s80, v1
	v_bfe_u32 v1, v39, 16, 1
	v_add3_u32 v1, v39, v1, s84
	v_bfe_u32 v3, v36, 16, 1
	v_lshrrev_b32_e32 v1, 16, v1
	v_add3_u32 v3, v36, v3, s84
	v_and_or_b32 v36, v3, s80, v1
	v_bfe_u32 v1, v38, 16, 1
	v_add3_u32 v1, v38, v1, s84
	v_bfe_u32 v3, v37, 16, 1
	v_lshrrev_b32_e32 v1, 16, v1
	v_add3_u32 v3, v37, v3, s84
	v_and_or_b32 v37, v3, s80, v1
	v_bfe_u32 v1, v51, 16, 1
	v_add3_u32 v1, v51, v1, s84
	v_bfe_u32 v3, v50, 16, 1
	v_lshrrev_b32_e32 v1, 16, v1
	v_add3_u32 v3, v50, v3, s84
	v_and_or_b32 v38, v3, s80, v1
	v_bfe_u32 v1, v49, 16, 1
	v_add3_u32 v1, v49, v1, s84
	v_bfe_u32 v3, v48, 16, 1
	v_lshrrev_b32_e32 v1, 16, v1
	v_add3_u32 v3, v48, v3, s84
	v_and_or_b32 v39, v3, s80, v1
	v_bfe_u32 v1, v55, 16, 1
	v_add3_u32 v1, v55, v1, s84
	v_bfe_u32 v3, v54, 16, 1
	v_lshrrev_b32_e32 v1, 16, v1
	v_add3_u32 v3, v54, v3, s84
	v_and_or_b32 v48, v3, s80, v1
	v_bfe_u32 v1, v53, 16, 1
	v_add3_u32 v1, v53, v1, s84
	v_bfe_u32 v3, v52, 16, 1
	v_lshrrev_b32_e32 v1, 16, v1
	v_add3_u32 v3, v52, v3, s84
	v_and_or_b32 v49, v3, s80, v1
	v_bfe_u32 v1, v59, 16, 1
	v_add3_u32 v1, v59, v1, s84
	v_bfe_u32 v3, v58, 16, 1
	v_lshrrev_b32_e32 v1, 16, v1
	v_add3_u32 v3, v58, v3, s84
	v_and_or_b32 v50, v3, s80, v1
	v_bfe_u32 v1, v57, 16, 1
	v_add3_u32 v1, v57, v1, s84
	v_bfe_u32 v3, v56, 16, 1
	v_lshrrev_b32_e32 v1, 16, v1
	v_add3_u32 v3, v56, v3, s84
	v_and_or_b32 v51, v3, s80, v1
	v_bfe_u32 v1, v77, 16, 1
	v_add3_u32 v1, v77, v1, s84
	v_bfe_u32 v3, v71, 16, 1
	v_lshrrev_b32_e32 v1, 16, v1
	v_add3_u32 v3, v71, v3, s84
	v_and_or_b32 v52, v3, s80, v1
	v_bfe_u32 v1, v69, 16, 1
	v_add3_u32 v1, v69, v1, s84
	v_bfe_u32 v3, v68, 16, 1
	v_lshrrev_b32_e32 v1, 16, v1
	v_add3_u32 v3, v68, v3, s84
	v_and_or_b32 v53, v3, s80, v1
	v_bfe_u32 v1, v91, 16, 1
	v_add3_u32 v1, v91, v1, s84
	v_bfe_u32 v3, v89, 16, 1
	v_lshrrev_b32_e32 v1, 16, v1
	v_add3_u32 v3, v89, v3, s84
	v_and_or_b32 v54, v3, s80, v1
	v_bfe_u32 v1, v88, 16, 1
	v_add3_u32 v1, v88, v1, s84
	v_bfe_u32 v3, v87, 16, 1
	v_lshrrev_b32_e32 v1, 16, v1
	v_add3_u32 v3, v87, v3, s84
	v_and_or_b32 v55, v3, s80, v1
	v_bfe_u32 v1, v98, 16, 1
	v_add3_u32 v1, v98, v1, s84
	v_bfe_u32 v3, v97, 16, 1
	v_lshrrev_b32_e32 v1, 16, v1
	v_add3_u32 v3, v97, v3, s84
	v_and_or_b32 v56, v3, s80, v1
	v_bfe_u32 v1, v95, 16, 1
	v_add3_u32 v1, v95, v1, s84
	v_bfe_u32 v3, v94, 16, 1
	v_lshrrev_b32_e32 v1, 16, v1
	v_add3_u32 v3, v94, v3, s84
	v_and_or_b32 v57, v3, s80, v1
	v_bfe_u32 v1, v104, 16, 1
	v_add3_u32 v1, v104, v1, s84
	v_bfe_u32 v3, v103, 16, 1
	v_lshrrev_b32_e32 v1, 16, v1
	v_add3_u32 v3, v103, v3, s84
	v_and_or_b32 v58, v3, s80, v1
	v_bfe_u32 v1, v102, 16, 1
	v_add3_u32 v1, v102, v1, s84
	v_bfe_u32 v3, v99, 16, 1
	v_lshrrev_b32_e32 v1, 16, v1
	v_add3_u32 v3, v99, v3, s84
	v_and_or_b32 v59, v3, s80, v1
	v_bfe_u32 v1, v67, 16, 1
	v_add3_u32 v1, v67, v1, s84
	v_bfe_u32 v3, v66, 16, 1
	v_lshrrev_b32_e32 v1, 16, v1
	v_add3_u32 v3, v66, v3, s84
	v_and_or_b32 v60, v3, s80, v1
	v_bfe_u32 v1, v64, 16, 1
	v_add3_u32 v1, v64, v1, s84
	v_bfe_u32 v3, v61, 16, 1
	v_lshrrev_b32_e32 v1, 16, v1
	v_add3_u32 v3, v61, v3, s84
	v_and_or_b32 v61, v3, s80, v1
	v_bfe_u32 v1, v82, 16, 1
	v_add3_u32 v1, v82, v1, s84
	v_bfe_u32 v3, v81, 16, 1
	v_lshrrev_b32_e32 v1, 16, v1
	v_add3_u32 v3, v81, v3, s84
	v_and_or_b32 v62, v3, s80, v1
	v_bfe_u32 v1, v79, 16, 1
	v_add3_u32 v1, v79, v1, s84
	v_bfe_u32 v3, v73, 16, 1
	v_lshrrev_b32_e32 v1, 16, v1
	v_add3_u32 v3, v73, v3, s84
; __device__ __forceinline__ unsigned pk2(float lo, float hi) { return f2bf(lo) | (f2bf(hi) << 16); }
; __device__ __forceinline__ void rglru_unit(LAS unsigned char* lds, int unit, const bf16* PBp, bf16* MGp, float* SSQRp, const float* cw, const float* cbias, const float* wa, const float* ba, const float* wx, const float* bxp, const float* lam) {
;     ...
;         for (int kk = 0; kk < 2; ++kk) { const float* wsrc = ((nb >> 1) ? wx : wa) + ((size_t)g * 64 + 32 * kk + 8 * fq) * 64 + hf * 32 + 16 * (nb & 1) + fr;
;             unsigned pk[4];
; #pragma unroll
;             for (int e = 0; e < 4; ++e) pk[e] = pk2(wsrc[(2 * e) * 64], wsrc[(2 * e + 1) * 64]);
;             wb[nb][kk] = __builtin_bit_cast(rg_bf16x8, (v4u){pk[0], pk[1], pk[2], pk[3]}); }
;     float gba[2], gbx[2], gsp[2];
; #pragma unroll
;     for (int cb = 0; cb < 2; ++cb) { const int cj = g * 64 + hf * 32 + 16 * cb + fr; gba[cb] = ba[cj]; gbx[cb] = bxp[cj]; const float lamj = lam[cj];
;         gsp[cb] = -8.0f * 1.4426950408889634f * ((lamj > 0.f) ? __logf(1.0f + __expf(-lamj)) : (-lamj + __logf(1.0f + __expf(lamj)))); }
;     const int ctt = tid >> 2, ch0 = (tid & 3) * 16;
;     const size_t rowb = (size_t)b * SEQ;
;     const bf16* xsrc = PBp + 1536 + g * 64 + ch0;
;     const bf16* gsrc = PBp + 2048 + g * 64 + hf * 32 + (tid & 3) * 8;
;     v4u xv[4][2]; v4u gv;
;     ...
;     RG_PREFETCH(0);
;     __syncthreads();
;     const int sc = tid & 31, ss = tid >> 5;
	v_and_or_b32 v63, v3, s80, v1
	v_bfe_u32 v1, v86, 16, 1
	v_add3_u32 v1, v86, v1, s84
	v_bfe_u32 v3, v85, 16, 1
	v_lshrrev_b32_e32 v1, 16, v1
	v_add3_u32 v3, v85, v3, s84
	v_and_or_b32 v64, v3, s80, v1
	v_bfe_u32 v1, v84, 16, 1
	v_add3_u32 v1, v84, v1, s84
	v_bfe_u32 v3, v83, 16, 1
	v_lshrrev_b32_e32 v1, 16, v1
	v_add3_u32 v3, v83, v3, s84
	v_and_or_b32 v65, v3, s80, v1
	v_bfe_u32 v1, v96, 16, 1
	v_add3_u32 v1, v96, v1, s84
	v_bfe_u32 v3, v93, 16, 1
	v_lshrrev_b32_e32 v1, 16, v1
	v_add3_u32 v3, v93, v3, s84
	v_and_or_b32 v66, v3, s80, v1
	v_bfe_u32 v1, v92, 16, 1
	s_add_u32 s2, s60, s4
	v_add3_u32 v1, v92, v1, s84
	v_bfe_u32 v3, v90, 16, 1
	s_addc_u32 s3, s61, 0
	s_lshl_b32 s4, s12, 1
	v_lshrrev_b32_e32 v1, 16, v1
	v_add3_u32 v3, v90, v3, s84
	s_add_u32 s2, s2, s4
	v_lshlrev_b32_e32 v2, 4, v105
	v_and_or_b32 v67, v3, s80, v1
	s_addc_u32 s3, s3, 0
	v_mov_b32_e32 v3, v0
	v_lshl_add_u64 v[68:69], s[2:3], 0, v[2:3]
	s_mov_b64 s[2:3], 0xe401000
	v_lshl_add_u64 v[68:69], v[68:69], 0, s[2:3]
	v_mad_i64_i32 v[68:69], s[2:3], v106, s71, v[68:69]
	global_load_dwordx4 v[68:71], v[68:69], off
	v_lshlrev_b32_e32 v73, 2, v2
	v_readlane_b32 s2, v255, 0
	v_and_b32_e32 v76, 16, v2
	v_lshlrev_b32_e32 v77, 1, v2
	v_add_u32_e32 v129, s2, v73
	s_add_i32 s2, 0, 0x11880
	v_add_u32_e32 v130, s2, v73
	v_lshrrev_b32_e32 v73, 1, v105
	v_cmp_eq_u32_e32 vcc, s52, v73
	v_lshl_add_u32 v73, v126, 7, 0
	v_lshl_add_u32 v131, v76, 2, v73
	v_lshlrev_b32_e32 v76, 4, v126
	v_add3_u32 v132, v73, v76, v77
	v_lshlrev_b32_e32 v73, 6, v126
	v_readlane_b32 s3, v255, 1
	v_and_b32_e32 v1, 31, v72
	s_movk_i32 s2, 0x90
	v_add3_u32 v133, s3, v73, v2
	v_lshl_or_b32 v73, s24, 4, v74
	v_mul_lo_u32 v73, v73, s2
	s_add_i32 s2, 0, 0x11800
	v_lshlrev_b32_e32 v79, 2, v1
	v_add_u32_e32 v135, s2, v79
	v_readlane_b32 s2, v255, 2
	v_lshlrev_b32_e32 v76, 4, v75
	v_lshlrev_b32_e32 v75, 7, v75
	v_add_u32_e32 v80, s2, v79
	s_movk_i32 s2, 0x80
	v_cmp_gt_i32_e64 s[6:7], s2, v72
	s_lshl_b32 s2, s24, 9
	v_ashrrev_i32_e32 v3, 5, v72
	v_or3_b32 v74, v75, s2, v74
	v_add3_u32 v134, 0, v73, v76
	v_lshlrev_b32_e32 v136, 3, v1
	v_lshlrev_b32_e32 v76, 3, v3
	v_lshlrev_b32_e32 v1, 1, v1
	v_lshl_add_u32 v138, v74, 2, 0
	v_lshl_or_b32 v74, v3, 10, v79
	s_movk_i32 s2, 0x420
	v_add_u32_e32 v137, s3, v1
	v_cmp_eq_u32_e64 s[4:5], 15, v3
	s_movk_i32 s3, 0x84
	v_add_u32_e32 v140, 0, v74
	v_cmp_lt_i32_e64 s[8:9], 0, v3
	v_cmp_lt_i32_e64 s[10:11], 1, v3
	v_cmp_lt_i32_e64 s[12:13], 2, v3
	v_cmp_lt_i32_e64 s[14:15], 3, v3
	v_cmp_lt_i32_e64 s[16:17], 4, v3
	v_cmp_lt_i32_e64 s[18:19], 5, v3
	v_cmp_lt_i32_e64 s[20:21], 6, v3
	v_cmp_lt_i32_e64 s[22:23], 7, v3
	v_cmp_lt_i32_e64 s[24:25], 8, v3
	v_cmp_lt_i32_e64 s[26:27], 9, v3
	v_cmp_lt_i32_e64 s[28:29], 10, v3
	v_cmp_lt_i32_e64 s[30:31], 11, v3
	v_cmp_lt_i32_e64 s[34:35], 12, v3
	v_cmp_lt_i32_e64 s[36:37], 13, v3
	v_cmp_lt_i32_e64 s[38:39], 14, v3
	v_lshlrev_b32_e32 v141, 9, v3
	v_mul_lo_u32 v3, v3, s2
	v_or_b32_e32 v74, 1, v76
	s_and_b32 s2, s45, 7
	v_mul_lo_u32 v81, v72, s3
	v_lshlrev_b32_e32 v75, 6, v74
	v_mul_lo_u32 v74, v74, s3
	s_lshl_b32 s2, s2, 12
	s_lshl_b32 s3, s64, 7
	s_add_i32 s53, s2, s3
	s_lshr_b32 s42, s53, 11
	s_lshl_b64 s[2:3], s[42:43], 17
	v_ashrrev_i32_e32 v73, 31, v72
	s_add_u32 s2, s2, 0x1d600000
	v_lshlrev_b32_e32 v78, 3, v72
	s_addc_u32 s3, s3, 0
	v_lshlrev_b64 v[72:73], 6, v[72:73]
	v_lshl_add_u64 v[102:103], s[2:3], 0, v[72:73]
	s_lshr_b32 s2, s45, 1
	v_ashrrev_i32_e32 v77, 31, v76
	v_and_or_b32 v72, s2, 56, v102
	v_lshl_or_b32 v102, s52, 2, v72
	s_lshl_b64 s[2:3], s[42:43], 22
	v_lshlrev_b64 v[72:73], 11, v[76:77]
	v_lshl_add_u64 v[104:105], s[2:3], 0, v[72:73]
	s_lshl_b32 s2, s45, 3
	s_and_b32 s2, s2, 0x380
	s_mul_hi_u32 s3, s42, 0xb00000
	s_mul_i32 s42, s42, 0xb00000
	v_or_b32_e32 v72, s2, v104
	s_lshl_b32 s45, s52, 6
	s_or_b32 s2, s42, s2
	s_add_u32 s2, s2, 0xe4b1000
	s_addc_u32 s3, s3, 0
	v_or3_b32 v104, v72, s45, v1
	v_mov_b64_e32 v[72:73], s[2:3]
	v_mul_f32_e32 v128, 0xc138aa3b, v107
	v_mad_i64_i32 v[106:107], s[2:3], v126, s71, v[72:73]
	v_or_b32_e32 v79, 0x80, v141
	v_or_b32_e32 v82, 0xc0, v141
	v_or_b32_e32 v83, 0x100, v141
	v_or_b32_e32 v84, 0x140, v141
	v_or_b32_e32 v85, 0x180, v141
	v_or_b32_e32 v86, 0x1c0, v141
	s_and_b32 s2, s53, 0xfffff800
	v_add_u32_e32 v1, 0, v81
	v_mul_f32_e32 v127, 0xc138aa3b, v108
	v_add_u32_e32 v139, 64, v138
	s_mov_b32 s44, 0
	v_or3_b32 v106, v106, s45, v2
	v_add_u32_e32 v142, s2, v126
	v_add_u32_e32 v143, s89, v78
	v_add_u32_e32 v144, v80, v3
	v_add_u32_e32 v145, v137, v75
	v_add_u32_e32 v146, v80, v74
	v_add_u32_e32 v147, v137, v79
	v_add_u32_e32 v148, v137, v82
	v_add_u32_e32 v149, v137, v83
	v_add_u32_e32 v150, v137, v84
	v_add_u32_e32 v151, v137, v85
	v_add_u32_e32 v152, v137, v86
	v_add_u32_e32 v153, 0x13d80, v1
	s_waitcnt vmcnt(0) lgkmcnt(0)
	s_barrier
	s_branch .LBB0_434

; #define LAS __attribute__((address_space(3)))
; __device__ __forceinline__ unsigned pk2(float lo, float hi) { return f2bf(lo) | (f2bf(hi) << 16); }
; __device__ __forceinline__ float bflo(unsigned u) { return __uint_as_float(u << 16); }
; __device__ __forceinline__ float bfhi(unsigned u) { return __uint_as_float(u & 0xffff0000u); }
; __device__ __forceinline__ void rglru_unit(LAS unsigned char* lds, int unit, const bf16* PBp, bf16* MGp, float* SSQRp, const float* cw, const float* cbias, const float* wa, const float* ba, const float* wx, const float* bxp, const float* lam) {
;     ...
;             unsigned pkx[8];
; #pragma unroll
;             for (int q4 = 0; q4 < 4; ++q4) {
;                 f32x4 o = *(const LAS f32x4*)(CW + 4 * 64 + ch0 + q4 * 4);
; #pragma unroll
;                 for (int k = 0; k < 4; ++k) { const f32x4 wv = *(const LAS f32x4*)(CW + k * 64 + ch0 + q4 * 4);
; #pragma unroll
;                     for (int e = 0; e < 4; ++e) { const int ch = q4 * 4 + e; const unsigned w = ((ch >> 3) ? xv[k][1] : xv[k][0])[(ch & 7) >> 1]; const float x = (ch & 1) ? bfhi(w) : bflo(w); o[e] = fmaf(wv[e], x, o[e]); } }
;                 pkx[2 * q4] = pk2(o[0], o[1]); pkx[2 * q4 + 1] = pk2(o[2], o[3]);
;                 if ((ch0 >> 5) == hf) *(LAS f32x4*)(XRF + ctt * 32 + (ch0 & 31) + q4 * 4) = o;
.LBB0_434:
	ds_read_b128 v[72:75], v129
	ds_read_b128 v[76:79], v130
	ds_read_b128 v[80:83], v130 offset:256
	ds_read_b128 v[84:87], v130 offset:512
	ds_read_b128 v[88:91], v130 offset:768
	s_waitcnt vmcnt(9)
	v_lshlrev_b32_e32 v3, 16, v5
	v_lshlrev_b32_e32 v2, 16, v4
	s_waitcnt lgkmcnt(3)
	v_mov_b32_e32 v92, v76
	v_mov_b32_e32 v93, v78
	v_mov_b32_e32 v94, v72
	v_mov_b32_e32 v95, v74
	v_pk_fma_f32 v[2:3], v[92:93], v[2:3], v[94:95]
	v_and_b32_e32 v93, 0xffff0000, v5
	v_and_b32_e32 v92, 0xffff0000, v4
	v_mov_b32_e32 v78, v77
	v_mov_b32_e32 v74, v73
	v_pk_fma_f32 v[72:73], v[78:79], v[92:93], v[74:75]
	v_lshlrev_b32_e32 v75, 16, v13
	v_lshlrev_b32_e32 v74, 16, v12
	s_waitcnt lgkmcnt(2)
	v_mov_b32_e32 v76, v80
	v_mov_b32_e32 v77, v82
	v_pk_fma_f32 v[2:3], v[76:77], v[74:75], v[2:3]
	v_and_b32_e32 v75, 0xffff0000, v13
	v_and_b32_e32 v74, 0xffff0000, v12
	v_mov_b32_e32 v82, v81
	v_pk_fma_f32 v[72:73], v[82:83], v[74:75], v[72:73]
	v_lshlrev_b32_e32 v75, 16, v25
	v_lshlrev_b32_e32 v74, 16, v24
	s_waitcnt lgkmcnt(1)
	v_mov_b32_e32 v76, v84
	v_mov_b32_e32 v77, v86
	v_pk_fma_f32 v[2:3], v[76:77], v[74:75], v[2:3]
	v_and_b32_e32 v75, 0xffff0000, v25
	v_and_b32_e32 v74, 0xffff0000, v24
	v_mov_b32_e32 v86, v85
	v_pk_fma_f32 v[72:73], v[86:87], v[74:75], v[72:73]
	v_lshlrev_b32_e32 v75, 16, v41
	v_lshlrev_b32_e32 v74, 16, v40
	s_waitcnt lgkmcnt(0)
	v_mov_b32_e32 v76, v88
	v_mov_b32_e32 v77, v90
	v_pk_fma_f32 v[2:3], v[76:77], v[74:75], v[2:3]
	v_and_b32_e32 v75, 0xffff0000, v41
	v_and_b32_e32 v74, 0xffff0000, v40
	v_mov_b32_e32 v90, v89
	v_pk_fma_f32 v[80:81], v[90:91], v[74:75], v[72:73]
	s_and_saveexec_b64 s[2:3], vcc
	v_mov_b32_e32 v72, v2
	v_mov_b32_e32 v73, v80
	v_mov_b32_e32 v74, v3
	v_mov_b32_e32 v75, v81
	ds_write_b128 v131, v[72:75] offset:18432
	s_or_b64 exec, exec, s[2:3]
	ds_read_b128 v[72:75], v129 offset:16
	ds_read_b128 v[76:79], v130 offset:16
	ds_read_b128 v[82:85], v130 offset:272
	ds_read_b128 v[86:89], v130 offset:528
	ds_read_b128 v[90:93], v130 offset:784
	v_lshlrev_b32_e32 v94, 16, v6
	v_and_b32_e32 v95, 0xffff0000, v6
	s_waitcnt lgkmcnt(3)
	v_pk_fma_f32 v[72:73], v[76:77], v[94:95], v[72:73]
	v_lshlrev_b32_e32 v76, 16, v14
	v_and_b32_e32 v77, 0xffff0000, v14
	s_waitcnt lgkmcnt(2)
	v_pk_fma_f32 v[72:73], v[82:83], v[76:77], v[72:73]
	v_lshlrev_b32_e32 v76, 16, v26
	v_and_b32_e32 v77, 0xffff0000, v26
	s_waitcnt lgkmcnt(1)
	v_pk_fma_f32 v[72:73], v[86:87], v[76:77], v[72:73]
	v_lshlrev_b32_e32 v76, 16, v42
	v_and_b32_e32 v77, 0xffff0000, v42
	s_waitcnt lgkmcnt(0)
	v_pk_fma_f32 v[72:73], v[90:91], v[76:77], v[72:73]
	v_lshlrev_b32_e32 v76, 16, v7
	v_and_b32_e32 v77, 0xffff0000, v7
	v_pk_fma_f32 v[74:75], v[78:79], v[76:77], v[74:75]
	v_lshlrev_b32_e32 v76, 16, v15
	v_and_b32_e32 v77, 0xffff0000, v15
	v_pk_fma_f32 v[74:75], v[84:85], v[76:77], v[74:75]
	v_lshlrev_b32_e32 v76, 16, v27
	v_and_b32_e32 v77, 0xffff0000, v27
	v_pk_fma_f32 v[74:75], v[88:89], v[76:77], v[74:75]
	v_lshlrev_b32_e32 v76, 16, v43
	v_and_b32_e32 v77, 0xffff0000, v43
	v_pk_fma_f32 v[74:75], v[92:93], v[76:77], v[74:75]
	s_and_saveexec_b64 s[2:3], vcc
	ds_write_b128 v131, v[72:75] offset:18448
	s_or_b64 exec, exec, s[2:3]
	ds_read_b128 v[76:79], v129 offset:32
	ds_read_b128 v[82:85], v130 offset:32
	ds_read_b128 v[86:89], v130 offset:288
	ds_read_b128 v[90:93], v130 offset:544
	ds_read_b128 v[94:97], v130 offset:800
	v_lshlrev_b32_e32 v99, 16, v9
	v_lshlrev_b32_e32 v98, 16, v8
	s_waitcnt lgkmcnt(3)
	v_mov_b32_e32 v108, v82
	v_mov_b32_e32 v109, v84
	v_mov_b32_e32 v110, v76
	v_mov_b32_e32 v111, v78
	v_pk_fma_f32 v[98:99], v[108:109], v[98:99], v[110:111]
	v_and_b32_e32 v109, 0xffff0000, v9
	v_and_b32_e32 v108, 0xffff0000, v8
	v_mov_b32_e32 v84, v83
	v_mov_b32_e32 v78, v77
	v_pk_fma_f32 v[76:77], v[84:85], v[108:109], v[78:79]
	v_lshlrev_b32_e32 v79, 16, v17
	v_lshlrev_b32_e32 v78, 16, v16
	s_waitcnt lgkmcnt(2)
	v_mov_b32_e32 v82, v86
	v_mov_b32_e32 v83, v88
	v_pk_fma_f32 v[78:79], v[82:83], v[78:79], v[98:99]
	v_and_b32_e32 v83, 0xffff0000, v17
	v_and_b32_e32 v82, 0xffff0000, v16
	v_mov_b32_e32 v88, v87
	v_pk_fma_f32 v[76:77], v[88:89], v[82:83], v[76:77]
	v_lshlrev_b32_e32 v83, 16, v29
	v_lshlrev_b32_e32 v82, 16, v28
	s_waitcnt lgkmcnt(1)
; #define LAS __attribute__((address_space(3)))
; __device__ __forceinline__ unsigned pk2(float lo, float hi) { return f2bf(lo) | (f2bf(hi) << 16); }
; __device__ __forceinline__ float bflo(unsigned u) { return __uint_as_float(u << 16); }
; __device__ __forceinline__ float bfhi(unsigned u) { return __uint_as_float(u & 0xffff0000u); }
; __device__ __forceinline__ void rglru_unit(LAS unsigned char* lds, int unit, const bf16* PBp, bf16* MGp, float* SSQRp, const float* cw, const float* cbias, const float* wa, const float* ba, const float* wx, const float* bxp, const float* lam) {
;     ...
;             for (int q4 = 0; q4 < 4; ++q4) {
;                 f32x4 o = *(const LAS f32x4*)(CW + 4 * 64 + ch0 + q4 * 4);
; #pragma unroll
;                 for (int k = 0; k < 4; ++k) { const f32x4 wv = *(const LAS f32x4*)(CW + k * 64 + ch0 + q4 * 4);
; #pragma unroll
;                     for (int e = 0; e < 4; ++e) { const int ch = q4 * 4 + e; const unsigned w = ((ch >> 3) ? xv[k][1] : xv[k][0])[(ch & 7) >> 1]; const float x = (ch & 1) ? bfhi(w) : bflo(w); o[e] = fmaf(wv[e], x, o[e]); } }
;                 pkx[2 * q4] = pk2(o[0], o[1]); pkx[2 * q4 + 1] = pk2(o[2], o[3]);
;                 if ((ch0 >> 5) == hf) *(LAS f32x4*)(XRF + ctt * 32 + (ch0 & 31) + q4 * 4) = o;
;             }
;             *(LAS v4u*)(XRB + ctt * 72 + ch0) = (v4u){pkx[0], pkx[1], pkx[2], pkx[3]};
;             *(LAS v4u*)(XRB + ctt * 72 + ch0 + 8) = (v4u){pkx[4], pkx[5], pkx[6], pkx[7]};
;             *(LAS v4u*)(GBL + ctt * 32 + (tid & 3) * 8) = gv;
;         }
;         if (ck < 15) RG_PREFETCH(t0 + 128);
	v_mov_b32_e32 v84, v90
	v_mov_b32_e32 v85, v92
	v_pk_fma_f32 v[78:79], v[84:85], v[82:83], v[78:79]
	v_and_b32_e32 v83, 0xffff0000, v29
	v_and_b32_e32 v82, 0xffff0000, v28
	v_mov_b32_e32 v92, v91
	v_pk_fma_f32 v[76:77], v[92:93], v[82:83], v[76:77]
	v_lshlrev_b32_e32 v83, 16, v45
	v_lshlrev_b32_e32 v82, 16, v44
	s_waitcnt lgkmcnt(0)
	v_mov_b32_e32 v84, v94
	v_mov_b32_e32 v85, v96
	v_pk_fma_f32 v[82:83], v[84:85], v[82:83], v[78:79]
	v_and_b32_e32 v79, 0xffff0000, v45
	v_and_b32_e32 v78, 0xffff0000, v44
	v_mov_b32_e32 v96, v95
	v_pk_fma_f32 v[84:85], v[96:97], v[78:79], v[76:77]
	s_and_saveexec_b64 s[2:3], vcc
	v_mov_b32_e32 v76, v82
	v_mov_b32_e32 v77, v84
	v_mov_b32_e32 v78, v83
	v_mov_b32_e32 v79, v85
	ds_write_b128 v131, v[76:79] offset:18464
	s_or_b64 exec, exec, s[2:3]
	ds_read_b128 v[76:79], v129 offset:48
	ds_read_b128 v[86:89], v130 offset:48
	ds_read_b128 v[90:93], v130 offset:304
	ds_read_b128 v[94:97], v130 offset:560
	ds_read_b128 v[108:111], v130 offset:816
	v_lshlrev_b32_e32 v98, 16, v10
	v_and_b32_e32 v99, 0xffff0000, v10
	s_waitcnt lgkmcnt(3)
	v_pk_fma_f32 v[76:77], v[86:87], v[98:99], v[76:77]
	v_lshlrev_b32_e32 v86, 16, v18
	v_and_b32_e32 v87, 0xffff0000, v18
	s_waitcnt lgkmcnt(2)
	v_pk_fma_f32 v[76:77], v[90:91], v[86:87], v[76:77]
	v_lshlrev_b32_e32 v86, 16, v30
	v_and_b32_e32 v87, 0xffff0000, v30
	s_waitcnt lgkmcnt(1)
	v_pk_fma_f32 v[76:77], v[94:95], v[86:87], v[76:77]
	v_lshlrev_b32_e32 v86, 16, v46
	v_and_b32_e32 v87, 0xffff0000, v46
	s_waitcnt lgkmcnt(0)
	v_pk_fma_f32 v[76:77], v[108:109], v[86:87], v[76:77]
	v_lshlrev_b32_e32 v86, 16, v11
	v_and_b32_e32 v87, 0xffff0000, v11
	v_pk_fma_f32 v[78:79], v[88:89], v[86:87], v[78:79]
	v_lshlrev_b32_e32 v86, 16, v19
	v_and_b32_e32 v87, 0xffff0000, v19
	v_pk_fma_f32 v[78:79], v[92:93], v[86:87], v[78:79]
	v_lshlrev_b32_e32 v86, 16, v31
	v_and_b32_e32 v87, 0xffff0000, v31
	v_pk_fma_f32 v[78:79], v[96:97], v[86:87], v[78:79]
	v_lshlrev_b32_e32 v86, 16, v47
	v_and_b32_e32 v87, 0xffff0000, v47
	v_pk_fma_f32 v[78:79], v[110:111], v[86:87], v[78:79]
	s_and_saveexec_b64 s[2:3], vcc
	ds_write_b128 v131, v[76:79] offset:18480
	s_or_b64 exec, exec, s[2:3]
	v_bfe_u32 v1, v77, 16, 1
	v_bfe_u32 v86, v85, 16, 1
	v_bfe_u32 v87, v84, 16, 1
	v_bfe_u32 v88, v79, 16, 1
	v_add3_u32 v79, v79, v88, s84
	v_add3_u32 v1, v77, v1, s84
	v_add3_u32 v84, v84, v87, s84
	v_add3_u32 v77, v85, v86, s84
	v_bfe_u32 v85, v78, 16, 1
	v_bfe_u32 v86, v76, 16, 1
	v_bfe_u32 v87, v82, 16, 1
	v_bfe_u32 v88, v83, 16, 1
	v_add3_u32 v83, v83, v88, s84
	v_add3_u32 v82, v82, v87, s84
	v_add3_u32 v76, v76, v86, s84
	v_add3_u32 v78, v78, v85, s84
	v_lshrrev_b32_e32 v85, 16, v78
	v_lshrrev_b32_e32 v78, 16, v76
	v_lshrrev_b32_e32 v76, 16, v82
	v_lshrrev_b32_e32 v82, 16, v83
	v_and_or_b32 v77, v77, s80, v82
	v_and_or_b32 v76, v84, s80, v76
	v_and_or_b32 v78, v1, s80, v78
	v_bfe_u32 v1, v73, 16, 1
	v_bfe_u32 v82, v81, 16, 1
	v_bfe_u32 v83, v80, 16, 1
	v_bfe_u32 v84, v75, 16, 1
	v_add3_u32 v75, v75, v84, s84
	v_add3_u32 v1, v73, v1, s84
	v_add3_u32 v80, v80, v83, s84
	v_add3_u32 v73, v81, v82, s84
	v_bfe_u32 v81, v74, 16, 1
	v_bfe_u32 v82, v72, 16, 1
	v_bfe_u32 v83, v2, 16, 1
	v_bfe_u32 v84, v3, 16, 1
	v_add3_u32 v3, v3, v84, s84
	v_add3_u32 v2, v2, v83, s84
	v_add3_u32 v72, v72, v82, s84
	v_add3_u32 v74, v74, v81, s84
	v_lshrrev_b32_e32 v81, 16, v74
	v_lshrrev_b32_e32 v74, 16, v72
	v_lshrrev_b32_e32 v2, 16, v2
	v_lshrrev_b32_e32 v3, 16, v3
	v_and_or_b32 v73, v73, s80, v3
	v_and_or_b32 v72, v80, s80, v2
	v_and_or_b32 v74, v1, s80, v74
	v_and_or_b32 v75, v75, s80, v81
	s_cmpk_lg_i32 s44, 0x780
	v_and_or_b32 v79, v79, s80, v85
	ds_write_b128 v132, v[72:75]
	ds_write_b128 v132, v[76:79] offset:16
	s_waitcnt vmcnt(8)
	ds_write_b128 v133, v[68:71]
	s_cbranch_scc0 .LBB0_452
	v_add_u32_e32 v1, s44, v126
	v_mov_b32_e32 v12, v0
	v_mov_b32_e32 v13, v0
	v_add_u32_e32 v40, 0x7d, v1
	v_mov_b32_e32 v14, v0
	v_mov_b32_e32 v15, v0
	v_mov_b64_e32 v[4:5], v[12:13]
	v_mov_b64_e32 v[8:9], v[12:13]
	v_cmp_lt_i32_e64 s[2:3], -1, v40
	v_add_u32_e32 v68, s44, v142
	v_mov_b64_e32 v[6:7], v[14:15]
	v_mov_b64_e32 v[10:11], v[14:15]
	s_and_saveexec_b64 s[62:63], s[2:3]
	s_cbranch_execz .LBB0_445
	v_add_u32_e32 v1, 0x7d, v68
	v_mad_u64_u32 v[2:3], s[2:3], v1, s71, v[100:101]
	global_load_dwordx4 v[8:11], v[2:3], off offset:16
	global_load_dwordx4 v[4:7], v[2:3], off

; #define LAS __attribute__((address_space(3)))
; __device__ __forceinline__ unsigned f2bf(float f) { unsigned u = __builtin_bit_cast(unsigned, f); return (u + 0x7fffu + ((u >> 16) & 1u)) >> 16; }
; __device__ __forceinline__ float fgelu_tanh(float x) { const float y = 0.7978845608028654f * (x + 0.044715f * x * x * x); const float t = 1.0f - 2.0f * __builtin_amdgcn_rcpf(__builtin_amdgcn_exp2f(2.8853900817779268f * y) + 1.0f); return 0.5f * x * (1.0f + t); }
; __device__ __forceinline__ void rglru_unit(LAS unsigned char* lds, int unit, const bf16* PBp, bf16* MGp, float* SSQRp, const float* cw, const float* cbias, const float* wa, const float* ba, const float* wx, const float* bxp, const float* lam) {
;     ...
;         float h = HIN[sc];
;         { typedef float f32x2v __attribute__((ext_vector_type(2))); f32x2v pe[15];
; #pragma unroll
;           for (int s2 = 0; s2 < 15; ++s2) pe[s2] = *(const LAS f32x2v*)(PE + (s2 * 32 + sc) * 2);
; #pragma unroll
;           for (int s2 = 0; s2 < 15; ++s2) h = (s2 < ss) ? fmaf(pe[s2].x, h, pe[s2].y) : h; }
;         bf16* orow = MGp + (rowb + t0 + ss * 8) * DM + 512 + g * 64 + hf * 32 + sc;
; #pragma unroll
;         for (int k = 0; k < 8; ++k) { h = av[k] * h + uv[k]; const float gbf = __uint_as_float((unsigned)GBL[(ss * 8 + k) * 32 + sc] << 16); const unsigned yb = f2bf(h * fgelu_tanh(gbf)); orow[(size_t)k * DM] = (bf16)yb;
;             const float yf = __uint_as_float(yb << 16); YSQ[(ss * 8 + k) * 33 + sc] = yf * yf; }
.LBB0_454:
	s_or_b64 exec, exec, s[2:3]
	s_waitcnt lgkmcnt(6)
	v_fma_f32 v96, v96, v1, v97
	v_cndmask_b32_e64 v1, v1, v96, s[10:11]
	v_fmac_f32_e32 v99, v98, v1
	v_cndmask_b32_e64 v1, v1, v99, s[12:13]
	s_waitcnt lgkmcnt(5)
	v_fma_f32 v92, v92, v1, v93
	v_cndmask_b32_e64 v1, v1, v92, s[14:15]
	v_fmac_f32_e32 v95, v94, v1
	v_cndmask_b32_e64 v1, v1, v95, s[16:17]
	s_waitcnt lgkmcnt(4)
	v_fma_f32 v88, v88, v1, v89
	v_cndmask_b32_e64 v1, v1, v88, s[18:19]
	v_fmac_f32_e32 v91, v90, v1
	v_cndmask_b32_e64 v1, v1, v91, s[20:21]
	s_waitcnt lgkmcnt(3)
	v_fma_f32 v84, v84, v1, v85
	v_cndmask_b32_e64 v1, v1, v84, s[22:23]
	v_fmac_f32_e32 v87, v86, v1
	v_cndmask_b32_e64 v1, v1, v87, s[24:25]
	s_waitcnt lgkmcnt(2)
	v_fma_f32 v80, v80, v1, v81
	v_cndmask_b32_e64 v1, v1, v80, s[26:27]
	v_fmac_f32_e32 v83, v82, v1
	v_cndmask_b32_e64 v1, v1, v83, s[28:29]
	s_waitcnt lgkmcnt(1)
	v_fma_f32 v76, v76, v1, v77
	v_cndmask_b32_e64 v1, v1, v76, s[30:31]
	v_fmac_f32_e32 v79, v78, v1
	v_add_u32_e32 v76, v137, v141
	v_cndmask_b32_e64 v1, v1, v79, s[34:35]
	ds_read_u16 v76, v76
	ds_read_u16 v77, v145
	ds_read_u16 v78, v147
	ds_read_u16 v79, v148
	ds_read_u16 v80, v149
	ds_read_u16 v81, v150
	ds_read_u16 v82, v151
	ds_read_u16 v83, v152
	s_waitcnt lgkmcnt(7)
	v_lshlrev_b32_e32 v76, 16, v76
	v_mul_f32_e32 v84, 0x3d372713, v76
	v_mul_f32_e32 v84, v84, v76
	v_fma_f32 v84, v84, v76, v76
	v_mul_f32_e32 v84, 0x3f4c422a, v84
	v_mul_f32_e32 v84, 0x4038aa3b, v84
	v_exp_f32_e32 v84, v84
	v_fma_f32 v72, v72, v1, v73
	v_cndmask_b32_e64 v1, v1, v72, s[36:37]
	v_fmac_f32_e32 v75, v74, v1
	v_add_f32_e32 v72, 1.0, v84
	v_rcp_f32_e32 v74, v72
	v_cndmask_b32_e64 v1, v1, v75, s[38:39]
	v_mul_f32_e32 v75, 0.5, v76
	v_fma_f32 v1, v120, v1, v118
	v_fma_f32 v74, v74, -2.0, 1.0
	v_add_f32_e32 v74, 1.0, v74
	v_mul_f32_e32 v74, v75, v74
	v_mul_f32_e32 v74, v74, v1
	v_bfe_u32 v75, v74, 16, 1
	s_waitcnt lgkmcnt(6)
	v_lshlrev_b32_e32 v77, 16, v77
	v_add3_u32 v76, v74, v75, s84
	v_mul_f32_e32 v74, 0x3d372713, v77
	v_mul_f32_e32 v74, v74, v77
	v_fma_f32 v74, v74, v77, v77
	v_mul_f32_e32 v74, 0x3f4c422a, v74
	v_mul_f32_e32 v74, 0x4038aa3b, v74
	v_exp_f32_e32 v84, v74
	v_lshl_add_u64 v[72:73], s[60:61], 0, v[104:105]
	s_mov_b32 s2, 0x19400000
	v_add_co_u32_e64 v74, s[2:3], s2, v72
	v_add_f32_e32 v84, 1.0, v84
	v_rcp_f32_e32 v84, v84
	v_addc_co_u32_e64 v75, s[2:3], 0, v73, s[2:3]
	global_store_short_d16_hi v[74:75], v76, off offset:1024
	v_and_b32_e32 v76, 0xffff0000, v76
	v_mul_f32_e32 v76, v76, v76
	v_fmac_f32_e32 v119, v121, v1
	v_fma_f32 v1, v84, -2.0, 1.0
	ds_write_b32 v144, v76
	v_mul_f32_e32 v76, 0.5, v77
	v_add_f32_e32 v1, 1.0, v1
	v_mul_f32_e32 v1, v76, v1
	s_waitcnt lgkmcnt(6)
	v_lshlrev_b32_e32 v76, 16, v78
	v_mul_f32_e32 v77, 0x3d372713, v76
	v_mul_f32_e32 v77, v77, v76
	v_fma_f32 v77, v77, v76, v76
	v_mul_f32_e32 v77, 0x3f4c422a, v77
	v_mul_f32_e32 v77, 0x4038aa3b, v77
	v_exp_f32_e32 v77, v77
	v_mul_f32_e32 v1, v1, v119
	v_bfe_u32 v78, v1, 16, 1
	v_add3_u32 v1, v1, v78, s84
	global_store_short_d16_hi v[74:75], v1, off offset:3072
	v_add_f32_e32 v74, 1.0, v77
	v_rcp_f32_e32 v74, v74
	v_mul_f32_e32 v75, 0.5, v76
	v_fma_f32 v77, v116, v119, v114
	s_waitcnt lgkmcnt(5)
	v_lshlrev_b32_e32 v78, 16, v79
	v_fma_f32 v74, v74, -2.0, 1.0
	v_add_f32_e32 v74, 1.0, v74
	v_mul_f32_e32 v74, v75, v74
	v_mul_f32_e32 v74, v74, v77
	v_bfe_u32 v75, v74, 16, 1
	v_add3_u32 v76, v74, v75, s84
	v_mul_f32_e32 v74, 0x3d372713, v78
	v_mul_f32_e32 v74, v74, v78
	v_fma_f32 v74, v74, v78, v78
	v_mul_f32_e32 v74, 0x3f4c422a, v74
	v_mul_f32_e32 v74, 0x4038aa3b, v74
	v_exp_f32_e32 v79, v74
	s_mov_b32 s2, 0x19401000
	v_add_co_u32_e64 v74, s[2:3], s2, v72
	v_add_f32_e32 v79, 1.0, v79
	v_rcp_f32_e32 v79, v79
	v_addc_co_u32_e64 v75, s[2:3], 0, v73, s[2:3]
	v_and_b32_e32 v1, 0xffff0000, v1
	global_store_short_d16_hi v[74:75], v76, off offset:1024
	v_and_b32_e32 v76, 0xffff0000, v76
	v_mul_f32_e32 v1, v1, v1
	v_mul_f32_e32 v76, v76, v76
	ds_write2_b32 v146, v1, v76 offset1:33
	v_fma_f32 v1, v79, -2.0, 1.0
	v_mul_f32_e32 v76, 0.5, v78
	v_add_f32_e32 v1, 1.0, v1
	v_mul_f32_e32 v1, v76, v1
	s_waitcnt lgkmcnt(5)
	v_lshlrev_b32_e32 v76, 16, v80
	v_fmac_f32_e32 v115, v117, v77
	v_mul_f32_e32 v77, 0x3d372713, v76
	v_mul_f32_e32 v77, v77, v76
	v_fma_f32 v77, v77, v76, v76
	v_mul_f32_e32 v77, 0x3f4c422a, v77
	v_mul_f32_e32 v77, 0x4038aa3b, v77
	v_exp_f32_e32 v77, v77
	v_mul_f32_e32 v1, v1, v115
	v_bfe_u32 v78, v1, 16, 1
	v_add3_u32 v1, v1, v78, s84
	global_store_short_d16_hi v[74:75], v1, off offset:3072
	v_add_f32_e32 v74, 1.0, v77
	v_rcp_f32_e32 v74, v74
	v_mul_f32_e32 v75, 0.5, v76
	v_fma_f32 v77, v112, v115, v110
	s_waitcnt lgkmcnt(4)
; __device__ __forceinline__ void rglru_unit(LAS unsigned char* lds, int unit, const bf16* PBp, bf16* MGp, float* SSQRp, const float* cw, const float* cbias, const float* wa, const float* ba, const float* wx, const float* bxp, const float* lam) {
;     ...
;         __syncthreads();
;         if (ss == 15) HIN[sc] = h;
;         if (tid < 128) { float sq = 0.f;
; #pragma unroll
;             for (int c2 = 0; c2 < 32; ++c2) sq += YSQ[tid * 33 + c2];
;             SSQRp[(rowb + t0 + tid) * 16 + g * 2 + hf] = sq; }
	v_lshlrev_b32_e32 v78, 16, v81
	v_fma_f32 v74, v74, -2.0, 1.0
	v_add_f32_e32 v74, 1.0, v74
	v_mul_f32_e32 v74, v75, v74
	v_mul_f32_e32 v74, v74, v77
	v_bfe_u32 v75, v74, 16, 1
	v_add3_u32 v76, v74, v75, s84
	v_mul_f32_e32 v74, 0x3d372713, v78
	v_mul_f32_e32 v74, v74, v78
	v_fma_f32 v74, v74, v78, v78
	v_mul_f32_e32 v74, 0x3f4c422a, v74
	v_mul_f32_e32 v74, 0x4038aa3b, v74
	v_exp_f32_e32 v79, v74
	s_mov_b32 s2, 0x19402000
	v_add_co_u32_e64 v74, s[2:3], s2, v72
	v_add_f32_e32 v79, 1.0, v79
	v_rcp_f32_e32 v79, v79
	v_addc_co_u32_e64 v75, s[2:3], 0, v73, s[2:3]
	v_and_b32_e32 v1, 0xffff0000, v1
	global_store_short_d16_hi v[74:75], v76, off offset:1024
	v_and_b32_e32 v76, 0xffff0000, v76
	v_mul_f32_e32 v1, v1, v1
	v_mul_f32_e32 v76, v76, v76
	ds_write2_b32 v146, v1, v76 offset0:66 offset1:99
	v_fma_f32 v1, v79, -2.0, 1.0
	v_mul_f32_e32 v76, 0.5, v78
	v_add_f32_e32 v1, 1.0, v1
	v_mul_f32_e32 v1, v76, v1
	s_waitcnt lgkmcnt(4)
	v_lshlrev_b32_e32 v76, 16, v82
	v_fmac_f32_e32 v111, v113, v77
	v_mul_f32_e32 v77, 0x3d372713, v76
	v_mul_f32_e32 v77, v77, v76
	v_fma_f32 v77, v77, v76, v76
	v_mul_f32_e32 v77, 0x3f4c422a, v77
	v_mul_f32_e32 v77, 0x4038aa3b, v77
	v_exp_f32_e32 v77, v77
	v_mul_f32_e32 v1, v1, v111
	v_bfe_u32 v78, v1, 16, 1
	v_add3_u32 v1, v1, v78, s84
	global_store_short_d16_hi v[74:75], v1, off offset:3072
	v_add_f32_e32 v74, 1.0, v77
	v_rcp_f32_e32 v74, v74
	v_mul_f32_e32 v75, 0.5, v76
	v_fma_f32 v2, v108, v111, v2
	s_mov_b32 s2, 0x19403000
	v_fma_f32 v74, v74, -2.0, 1.0
	v_add_f32_e32 v74, 1.0, v74
	v_mul_f32_e32 v74, v75, v74
	v_mul_f32_e32 v74, v74, v2
	v_bfe_u32 v75, v74, 16, 1
	v_add3_u32 v74, v74, v75, s84
	s_waitcnt lgkmcnt(3)
	v_lshlrev_b32_e32 v75, 16, v83
	v_mul_f32_e32 v76, 0x3d372713, v75
	v_mul_f32_e32 v76, v76, v75
	v_fma_f32 v76, v76, v75, v75
	v_mul_f32_e32 v76, 0x3f4c422a, v76
	v_mul_f32_e32 v76, 0x4038aa3b, v76
	v_exp_f32_e32 v76, v76
	v_add_co_u32_e64 v72, s[2:3], s2, v72
	v_and_b32_e32 v1, 0xffff0000, v1
	v_add_f32_e32 v76, 1.0, v76
	v_rcp_f32_e32 v76, v76
	v_addc_co_u32_e64 v73, s[2:3], 0, v73, s[2:3]
	global_store_short_d16_hi v[72:73], v74, off offset:1024
	v_and_b32_e32 v74, 0xffff0000, v74
	v_mul_f32_e32 v1, v1, v1
	v_mul_f32_e32 v74, v74, v74
	ds_write2_b32 v146, v1, v74 offset0:132 offset1:165
	v_fma_f32 v1, v76, -2.0, 1.0
	v_fmac_f32_e32 v3, v109, v2
	v_mul_f32_e32 v2, 0.5, v75
	v_add_f32_e32 v1, 1.0, v1
	v_mul_f32_e32 v1, v2, v1
	v_mul_f32_e32 v1, v1, v3
	v_bfe_u32 v2, v1, 16, 1
	v_add3_u32 v1, v1, v2, s84
	global_store_short_d16_hi v[72:73], v1, off offset:3072
	v_and_b32_e32 v1, 0xffff0000, v1
	v_mul_f32_e32 v1, v1, v1
	ds_write_b32 v146, v1 offset:792
	s_waitcnt lgkmcnt(0)
	s_barrier
	s_and_saveexec_b64 s[2:3], s[4:5]
	ds_write_b32 v135, v3
	s_or_b64 exec, exec, s[2:3]
	s_and_saveexec_b64 s[2:3], s[6:7]
	s_cbranch_execz .LBB0_433
	ds_read2_b32 v[76:77], v153 offset1:1
	ds_read2_b32 v[78:79], v153 offset0:2 offset1:3
	ds_read2_b32 v[80:81], v153 offset0:4 offset1:5
	ds_read2_b32 v[82:83], v153 offset0:6 offset1:7
	ds_read2_b32 v[84:85], v153 offset0:8 offset1:9
	ds_read2_b32 v[86:87], v153 offset0:10 offset1:11
	ds_read2_b32 v[88:89], v153 offset0:12 offset1:13
	ds_read2_b32 v[90:91], v153 offset0:14 offset1:15
	ds_read2_b32 v[92:93], v153 offset0:16 offset1:17
	ds_read2_b32 v[94:95], v153 offset0:18 offset1:19
	ds_read2_b32 v[96:97], v153 offset0:20 offset1:21
	ds_read2_b32 v[98:99], v153 offset0:22 offset1:23
	s_waitcnt lgkmcnt(4)
	ds_read2_b32 v[108:109], v153 offset0:24 offset1:25
	ds_read2_b32 v[110:111], v153 offset0:26 offset1:27
	ds_read2_b32 v[112:113], v153 offset0:28 offset1:29
	ds_read2_b32 v[114:115], v153 offset0:30 offset1:31
	v_add_f32_e32 v1, 0, v76
	v_add_f32_e32 v1, v1, v77
	v_add_f32_e32 v1, v1, v78
	v_add_f32_e32 v1, v1, v79
	v_add_f32_e32 v1, v1, v80
	v_add_f32_e32 v1, v1, v81
	v_add_f32_e32 v1, v1, v82
	v_add_f32_e32 v1, v1, v83
	v_add_f32_e32 v1, v1, v84
	v_add_f32_e32 v1, v1, v85
	v_add_f32_e32 v1, v1, v86
	v_add_f32_e32 v1, v1, v87
	v_add_f32_e32 v1, v1, v88
	v_add_f32_e32 v1, v1, v89
	v_add_f32_e32 v1, v1, v90
	v_add_f32_e32 v1, v1, v91
	s_waitcnt lgkmcnt(0)
	v_add_f32_e32 v1, v1, v92
	v_add_f32_e32 v1, v1, v93
	v_add_f32_e32 v1, v1, v94
	v_add_f32_e32 v1, v1, v95
	v_add_f32_e32 v1, v1, v96
	v_add_f32_e32 v1, v1, v97
	v_add_f32_e32 v1, v1, v98
	v_add_f32_e32 v1, v1, v99
	v_add_f32_e32 v1, v1, v108
	v_add_f32_e32 v1, v1, v109
	v_add_f32_e32 v1, v1, v110
	v_add_f32_e32 v1, v1, v111
	v_add_f32_e32 v1, v1, v112
	v_add_f32_e32 v1, v1, v113
	v_add_f32_e32 v1, v1, v114
	v_add_f32_e32 v1, v1, v115
	v_lshl_add_u64 v[2:3], s[60:61], 0, v[102:103]
	global_store_dword v[2:3], v1, off
	s_branch .LBB0_433
